# phase-2 work queue lookahead plus early publish of the prefetched ticket in LDS: fast-path dequeue is one barrier and one LDS read
# baseline (speedup 1.0000x reference)
.LBB0_269:
	s_barrier
	s_cmp_eq_u32 s99, 1
	s_cbranch_scc0 .Ldq_slow
	s_mov_b32 s99, 0
	ds_read_b32 v2, v1 offset:8
	s_branch .Ldq_join
.Ldq_slow:
	s_mov_b64 s[0:1], exec
	v_readlane_b32 s4, v197, 0
	v_readlane_b32 s5, v197, 1
	s_and_b64 s[4:5], s[0:1], s[4:5]
	s_mov_b64 exec, s[4:5]
	s_cbranch_execz .LBB0_273
	s_mov_b64 s[6:7], exec
	v_mbcnt_lo_u32_b32 v2, s6, 0
	v_mbcnt_hi_u32_b32 v2, s7, v2
	v_cmp_eq_u32_e32 vcc, 0, v2
	s_and_saveexec_b64 s[4:5], vcc
	s_cbranch_execz .LBB0_272
	s_bcnt1_i32_b64 s6, s[6:7]
	v_mov_b32_e32 v3, s6
	global_atomic_add v3, v99, v3, s[92:93] offset:8 sc0

.Ldq_join:
	s_movk_i32 s0, 0x8f3
	s_waitcnt lgkmcnt(0)
	v_cmp_lt_i32_e32 vcc, s0, v2
	v_readfirstlane_b32 s58, v2
	s_mov_b64 s[0:1], -1
	s_cbranch_vccnz .LBB0_268
	s_cmpk_lt_i32 s58, 0x144
	s_mov_b64 s[4:5], -1
	s_cbranch_scc1 .LBB0_295
	s_add_i32 s0, s58, 0xfebc
	s_and_b32 s1, s0, 0xffff
	s_mul_i32 s1, s1, 0x8f9d
	s_lshr_b32 s1, s1, 16
	s_sub_i32 s4, s0, s1
	s_bfe_u32 s4, s4, 0xf0001
	s_add_i32 s4, s4, s1
	s_bfe_u32 s6, s4, 0xb0005
	s_mul_i32 s1, s6, 41
	s_sub_i32 s18, s0, s1
	s_lshl_b32 s0, s18, 4
	s_and_b32 s1, s0, 0xfff0
	s_add_i32 s0, s0, 16
	s_and_b32 s0, s0, 0xfff0
	s_mul_i32 s1, s1, 0xc7cf
	s_mul_i32 s0, s0, 0xc7cf
	s_lshr_b32 s7, s1, 21
	s_lshr_b32 s4, s0, 21
	s_cmp_le_u32 s4, s7
	s_cselect_b64 s[4:5], -1, 0
	s_mov_b64 s[0:1], -1
	s_and_b64 vcc, exec, s[4:5]
	s_cbranch_vccz .LBB0_277
	s_addk_i32 s18, 0x144
	s_mul_i32 s0, s6, 25
	s_and_b32 s1, s18, 0xffff
	s_add_i32 s0, s0, s1
	s_sub_i32 s58, s0, s7
	s_mov_b64 s[0:1], 0

.Ldq_skip0:
	s_mov_b64 exec, s[8:9]
	s_mov_b32 s99, 1
	ds_read_b128 v[72:75], v16
	ds_read_b128 v[76:79], v16 offset:2048
	ds_read_b128 v[106:109], v16 offset:4096
	ds_read_b128 v[112:115], v16 offset:6144
	ds_read_b128 v[116:119], v17
	ds_read_b128 v[120:123], v17 offset:2048
	ds_read_b128 v[124:127], v17 offset:4096
	ds_read_b128 v[128:131], v17 offset:6144
	s_waitcnt lgkmcnt(8)
	v_mfma_f32_16x16x32_bf16 v[84:87], v[152:155], v[102:105], v[84:87]
	v_mfma_f32_16x16x32_bf16 v[88:91], v[156:159], v[102:105], v[88:91]
	v_mfma_f32_16x16x32_bf16 v[92:95], v[160:163], v[102:105], v[92:95]
	v_mfma_f32_16x16x32_bf16 v[22:25], v[164:167], v[102:105], v[22:25]
	v_mfma_f32_16x16x32_bf16 v[38:41], v[152:155], v[132:135], v[38:41]
	v_mfma_f32_16x16x32_bf16 v[46:49], v[156:159], v[132:135], v[46:49]
	v_mfma_f32_16x16x32_bf16 v[58:61], v[160:163], v[132:135], v[58:61]
	v_mfma_f32_16x16x32_bf16 v[50:53], v[164:167], v[132:135], v[50:53]
	v_mfma_f32_16x16x32_bf16 v[42:45], v[152:155], v[138:141], v[42:45]
	v_mfma_f32_16x16x32_bf16 v[62:65], v[156:159], v[138:141], v[62:65]
	v_mfma_f32_16x16x32_bf16 v[66:69], v[160:163], v[138:141], v[66:69]
	v_mfma_f32_16x16x32_bf16 v[54:57], v[164:167], v[138:141], v[54:57]
	v_mfma_f32_16x16x32_bf16 v[34:37], v[152:155], v[142:145], v[34:37]
	v_mfma_f32_16x16x32_bf16 v[30:33], v[156:159], v[142:145], v[30:33]
	v_mfma_f32_16x16x32_bf16 v[26:29], v[160:163], v[142:145], v[26:29]
	v_mfma_f32_16x16x32_bf16 v[18:21], v[164:167], v[142:145], v[18:21]
	s_waitcnt vmcnt(6) lgkmcnt(0)
	s_barrier
	ds_read_b128 v[102:105], v8
	ds_read_b128 v[132:135], v8 offset:2048
	ds_read_b128 v[138:141], v8 offset:4096
	ds_read_b128 v[142:145], v8 offset:6144
	ds_read_b128 v[152:155], v9 offset:16384
	ds_read_b128 v[156:159], v9 offset:18432
	ds_read_b128 v[160:163], v9 offset:20480
	ds_read_b128 v[164:167], v9 offset:22528
	v_mfma_f32_16x16x32_bf16 v[84:87], v[116:119], v[72:75], v[84:87]
	v_mfma_f32_16x16x32_bf16 v[88:91], v[120:123], v[72:75], v[88:91]
	v_mfma_f32_16x16x32_bf16 v[92:95], v[124:127], v[72:75], v[92:95]
	v_mfma_f32_16x16x32_bf16 v[22:25], v[128:131], v[72:75], v[22:25]
	v_mfma_f32_16x16x32_bf16 v[38:41], v[116:119], v[76:79], v[38:41]
	v_mfma_f32_16x16x32_bf16 v[46:49], v[120:123], v[76:79], v[46:49]
	v_mfma_f32_16x16x32_bf16 v[58:61], v[124:127], v[76:79], v[58:61]
	v_mfma_f32_16x16x32_bf16 v[50:53], v[128:131], v[76:79], v[50:53]
	v_mfma_f32_16x16x32_bf16 v[42:45], v[116:119], v[106:109], v[42:45]
	v_mfma_f32_16x16x32_bf16 v[62:65], v[120:123], v[106:109], v[62:65]
	v_mfma_f32_16x16x32_bf16 v[66:69], v[124:127], v[106:109], v[66:69]
	v_mfma_f32_16x16x32_bf16 v[54:57], v[128:131], v[106:109], v[54:57]
	v_mfma_f32_16x16x32_bf16 v[34:37], v[116:119], v[112:115], v[34:37]
	v_mfma_f32_16x16x32_bf16 v[30:33], v[120:123], v[112:115], v[30:33]
	v_mfma_f32_16x16x32_bf16 v[26:29], v[124:127], v[112:115], v[26:29]
	v_mfma_f32_16x16x32_bf16 v[18:21], v[128:131], v[112:115], v[18:21]
	s_mov_b64 s[8:9], 0x700
	s_mov_b32 m0, s63
	v_lshl_add_u64 v[72:73], v[2:3], 0, s[8:9]
	global_load_lds_dwordx4 v[72:73], off
	v_lshl_add_u64 v[72:73], v[4:5], 0, s[8:9]
	s_mov_b32 m0, s64
	s_nop 0
	global_load_lds_dwordx4 v[72:73], off
	v_lshl_add_u64 v[72:73], v[6:7], 0, s[8:9]
	s_mov_b32 m0, s72
	s_mov_b64 s[8:9], 0x20700
	global_load_lds_dwordx4 v[72:73], off
	v_lshl_add_u64 v[72:73], v[6:7], 0, s[8:9]
	s_mov_b32 m0, s73
	s_mov_b64 s[8:9], 0x40700
	global_load_lds_dwordx4 v[72:73], off
	v_lshl_add_u64 v[72:73], v[6:7], 0, s[8:9]
	s_mov_b32 m0, s74
	s_mov_b64 s[8:9], 0x60700
	global_load_lds_dwordx4 v[72:73], off
	v_lshl_add_u64 v[72:73], v[6:7], 0, s[8:9]
	s_mov_b32 m0, s75
	s_nop 0
	global_load_lds_dwordx4 v[72:73], off
	ds_read_b128 v[72:75], v10
	ds_read_b128 v[76:79], v10 offset:2048
	ds_read_b128 v[106:109], v10 offset:4096
	ds_read_b128 v[112:115], v10 offset:6144
	ds_read_b128 v[116:119], v11 offset:16384
	ds_read_b128 v[120:123], v11 offset:18432
	ds_read_b128 v[124:127], v11 offset:20480
	ds_read_b128 v[128:131], v11 offset:22528
	s_waitcnt lgkmcnt(8)
	v_mfma_f32_16x16x32_bf16 v[84:87], v[152:155], v[102:105], v[84:87]
	v_mfma_f32_16x16x32_bf16 v[88:91], v[156:159], v[102:105], v[88:91]
	v_mfma_f32_16x16x32_bf16 v[92:95], v[160:163], v[102:105], v[92:95]
	v_mfma_f32_16x16x32_bf16 v[22:25], v[164:167], v[102:105], v[22:25]
	v_mfma_f32_16x16x32_bf16 v[38:41], v[152:155], v[132:135], v[38:41]
	v_mfma_f32_16x16x32_bf16 v[46:49], v[156:159], v[132:135], v[46:49]
	v_mfma_f32_16x16x32_bf16 v[58:61], v[160:163], v[132:135], v[58:61]
	v_mfma_f32_16x16x32_bf16 v[50:53], v[164:167], v[132:135], v[50:53]
	v_mfma_f32_16x16x32_bf16 v[42:45], v[152:155], v[138:141], v[42:45]
	v_mfma_f32_16x16x32_bf16 v[62:65], v[156:159], v[138:141], v[62:65]
	v_mfma_f32_16x16x32_bf16 v[66:69], v[160:163], v[138:141], v[66:69]
	v_mfma_f32_16x16x32_bf16 v[54:57], v[164:167], v[138:141], v[54:57]
	v_mfma_f32_16x16x32_bf16 v[34:37], v[152:155], v[142:145], v[34:37]
	v_mfma_f32_16x16x32_bf16 v[30:33], v[156:159], v[142:145], v[30:33]
	v_mfma_f32_16x16x32_bf16 v[26:29], v[160:163], v[142:145], v[26:29]
	v_mfma_f32_16x16x32_bf16 v[18:21], v[164:167], v[142:145], v[18:21]
	s_waitcnt vmcnt(6) lgkmcnt(0)
	s_barrier
	ds_read_b128 v[102:105], v8 offset:49152
	ds_read_b128 v[132:135], v8 offset:51200
	ds_read_b128 v[138:141], v8 offset:53248
	ds_read_b128 v[142:145], v8 offset:55296
	ds_read_b128 v[152:155], v12
	ds_read_b128 v[156:159], v12 offset:2048
	ds_read_b128 v[160:163], v12 offset:4096
	ds_read_b128 v[164:167], v12 offset:6144
	v_mfma_f32_16x16x32_bf16 v[84:87], v[116:119], v[72:75], v[84:87]
	v_mfma_f32_16x16x32_bf16 v[88:91], v[120:123], v[72:75], v[88:91]
	v_mfma_f32_16x16x32_bf16 v[92:95], v[124:127], v[72:75], v[92:95]
	v_mfma_f32_16x16x32_bf16 v[22:25], v[128:131], v[72:75], v[22:25]
	v_mfma_f32_16x16x32_bf16 v[38:41], v[116:119], v[76:79], v[38:41]
	v_mfma_f32_16x16x32_bf16 v[46:49], v[120:123], v[76:79], v[46:49]
	v_mfma_f32_16x16x32_bf16 v[58:61], v[124:127], v[76:79], v[58:61]
	v_mfma_f32_16x16x32_bf16 v[50:53], v[128:131], v[76:79], v[50:53]
	v_mfma_f32_16x16x32_bf16 v[42:45], v[116:119], v[106:109], v[42:45]
	v_mfma_f32_16x16x32_bf16 v[62:65], v[120:123], v[106:109], v[62:65]
	v_mfma_f32_16x16x32_bf16 v[66:69], v[124:127], v[106:109], v[66:69]
	v_mfma_f32_16x16x32_bf16 v[54:57], v[128:131], v[106:109], v[54:57]
	v_mfma_f32_16x16x32_bf16 v[34:37], v[116:119], v[112:115], v[34:37]
	v_mfma_f32_16x16x32_bf16 v[30:33], v[120:123], v[112:115], v[30:33]
	v_mfma_f32_16x16x32_bf16 v[26:29], v[124:127], v[112:115], v[26:29]
	v_mfma_f32_16x16x32_bf16 v[18:21], v[128:131], v[112:115], v[18:21]
	s_mov_b64 s[8:9], 0x780
	s_mov_b32 m0, s56
	v_lshl_add_u64 v[2:3], v[2:3], 0, s[8:9]
	global_load_lds_dwordx4 v[2:3], off
	v_lshl_add_u64 v[2:3], v[4:5], 0, s[8:9]
	s_mov_b32 m0, s1
	s_nop 0
	global_load_lds_dwordx4 v[2:3], off
	v_lshl_add_u64 v[2:3], v[6:7], 0, s[8:9]
	s_mov_b32 m0, s5
	s_mov_b64 s[8:9], 0x20780
	global_load_lds_dwordx4 v[2:3], off
	v_lshl_add_u64 v[2:3], v[6:7], 0, s[8:9]
	s_mov_b32 m0, s33
	s_mov_b64 s[8:9], 0x40780
	global_load_lds_dwordx4 v[2:3], off
	v_lshl_add_u64 v[2:3], v[6:7], 0, s[8:9]
	s_mov_b32 m0, s38
	s_mov_b64 s[8:9], 0x60780
	global_load_lds_dwordx4 v[2:3], off
	v_lshl_add_u64 v[2:3], v[6:7], 0, s[8:9]
	s_mov_b32 m0, s39
	s_nop 0
	global_load_lds_dwordx4 v[2:3], off
	ds_read_b128 v[2:5], v10 offset:49152
	ds_read_b128 v[72:75], v10 offset:51200
	ds_read_b128 v[76:79], v10 offset:53248
	ds_read_b128 v[106:109], v10 offset:55296
	ds_read_b128 v[112:115], v13
	ds_read_b128 v[116:119], v13 offset:2048
	ds_read_b128 v[120:123], v13 offset:4096
	ds_read_b128 v[124:127], v13 offset:6144
	s_waitcnt lgkmcnt(8)
	v_mfma_f32_16x16x32_bf16 v[84:87], v[152:155], v[102:105], v[84:87]
	v_mfma_f32_16x16x32_bf16 v[88:91], v[156:159], v[102:105], v[88:91]
	v_mfma_f32_16x16x32_bf16 v[92:95], v[160:163], v[102:105], v[92:95]
	v_mfma_f32_16x16x32_bf16 v[22:25], v[164:167], v[102:105], v[22:25]
	v_mfma_f32_16x16x32_bf16 v[38:41], v[152:155], v[132:135], v[38:41]
	v_mfma_f32_16x16x32_bf16 v[46:49], v[156:159], v[132:135], v[46:49]
	v_mfma_f32_16x16x32_bf16 v[58:61], v[160:163], v[132:135], v[58:61]
	v_mfma_f32_16x16x32_bf16 v[50:53], v[164:167], v[132:135], v[50:53]
	v_mfma_f32_16x16x32_bf16 v[42:45], v[152:155], v[138:141], v[42:45]
	v_mfma_f32_16x16x32_bf16 v[62:65], v[156:159], v[138:141], v[62:65]
	v_mfma_f32_16x16x32_bf16 v[66:69], v[160:163], v[138:141], v[66:69]
	v_mfma_f32_16x16x32_bf16 v[54:57], v[164:167], v[138:141], v[54:57]
	v_mfma_f32_16x16x32_bf16 v[34:37], v[152:155], v[142:145], v[34:37]
	v_mfma_f32_16x16x32_bf16 v[30:33], v[156:159], v[142:145], v[30:33]
	v_mfma_f32_16x16x32_bf16 v[26:29], v[160:163], v[142:145], v[26:29]
	v_mfma_f32_16x16x32_bf16 v[18:21], v[164:167], v[142:145], v[18:21]
	s_waitcnt vmcnt(6) lgkmcnt(0)
	s_barrier
	ds_read_b128 v[102:105], v14
	ds_read_b128 v[128:131], v14 offset:2048
	ds_read_b128 v[132:135], v14 offset:4096
	ds_read_b128 v[138:141], v14 offset:6144
	ds_read_b128 v[142:145], v15
	ds_read_b128 v[152:155], v15 offset:2048
	ds_read_b128 v[156:159], v15 offset:4096
	ds_read_b128 v[12:15], v15 offset:6144
	v_mfma_f32_16x16x32_bf16 v[84:87], v[112:115], v[2:5], v[84:87]
	v_mfma_f32_16x16x32_bf16 v[88:91], v[116:119], v[2:5], v[88:91]
	v_mfma_f32_16x16x32_bf16 v[92:95], v[120:123], v[2:5], v[92:95]
	v_mfma_f32_16x16x32_bf16 v[2:5], v[124:127], v[2:5], v[22:25]
	v_mfma_f32_16x16x32_bf16 v[22:25], v[112:115], v[72:75], v[38:41]
	v_mfma_f32_16x16x32_bf16 v[38:41], v[116:119], v[72:75], v[46:49]
	v_mfma_f32_16x16x32_bf16 v[46:49], v[120:123], v[72:75], v[58:61]
	v_mfma_f32_16x16x32_bf16 v[50:53], v[124:127], v[72:75], v[50:53]
	v_mfma_f32_16x16x32_bf16 v[42:45], v[112:115], v[76:79], v[42:45]
	v_mfma_f32_16x16x32_bf16 v[58:61], v[116:119], v[76:79], v[62:65]
	v_mfma_f32_16x16x32_bf16 v[62:65], v[120:123], v[76:79], v[66:69]
	v_mfma_f32_16x16x32_bf16 v[54:57], v[124:127], v[76:79], v[54:57]
	v_mfma_f32_16x16x32_bf16 v[34:37], v[112:115], v[106:109], v[34:37]
	v_mfma_f32_16x16x32_bf16 v[30:33], v[116:119], v[106:109], v[30:33]
	v_mfma_f32_16x16x32_bf16 v[26:29], v[120:123], v[106:109], v[26:29]
	v_mfma_f32_16x16x32_bf16 v[18:21], v[124:127], v[106:109], v[18:21]
	ds_read_b128 v[66:69], v16
	ds_read_b128 v[72:75], v16 offset:2048
	ds_read_b128 v[76:79], v16 offset:4096
	ds_read_b128 v[106:109], v16 offset:6144
	ds_read_b128 v[112:115], v17
	ds_read_b128 v[116:119], v17 offset:2048
	ds_read_b128 v[120:123], v17 offset:4096
	ds_read_b128 v[124:127], v17 offset:6144
	s_waitcnt lgkmcnt(8)
	v_mfma_f32_16x16x32_bf16 v[84:87], v[142:145], v[102:105], v[84:87]
	v_mfma_f32_16x16x32_bf16 v[88:91], v[152:155], v[102:105], v[88:91]
	v_mfma_f32_16x16x32_bf16 v[92:95], v[156:159], v[102:105], v[92:95]
	v_mfma_f32_16x16x32_bf16 v[2:5], v[12:15], v[102:105], v[2:5]
	v_mfma_f32_16x16x32_bf16 v[22:25], v[142:145], v[128:131], v[22:25]
	v_mfma_f32_16x16x32_bf16 v[38:41], v[152:155], v[128:131], v[38:41]
	v_mfma_f32_16x16x32_bf16 v[46:49], v[156:159], v[128:131], v[46:49]
	v_mfma_f32_16x16x32_bf16 v[50:53], v[12:15], v[128:131], v[50:53]
	v_mfma_f32_16x16x32_bf16 v[42:45], v[142:145], v[132:135], v[42:45]
	v_mfma_f32_16x16x32_bf16 v[58:61], v[152:155], v[132:135], v[58:61]
	v_mfma_f32_16x16x32_bf16 v[62:65], v[156:159], v[132:135], v[62:65]
	v_mfma_f32_16x16x32_bf16 v[54:57], v[12:15], v[132:135], v[54:57]
	v_mfma_f32_16x16x32_bf16 v[34:37], v[142:145], v[138:141], v[34:37]
	v_mfma_f32_16x16x32_bf16 v[30:33], v[152:155], v[138:141], v[30:33]
	v_mfma_f32_16x16x32_bf16 v[26:29], v[156:159], v[138:141], v[26:29]
	v_mfma_f32_16x16x32_bf16 v[12:15], v[12:15], v[138:141], v[18:21]
	s_waitcnt vmcnt(0) lgkmcnt(0)
	s_barrier
	s_mov_b64 s[8:9], exec
	v_readlane_b32 s20, v197, 0
	v_readlane_b32 s21, v197, 1
	s_and_b64 s[20:21], s[8:9], s[20:21]
	s_mov_b64 exec, s[20:21]
	s_cbranch_execz .Ldq_pskip0
	v_mov_b32_e32 v253, 0x24008
	ds_write_b32 v253, v250
.Ldq_pskip0:
	s_mov_b64 exec, s[8:9]
	s_nop 1
	ds_read_b128 v[16:19], v8
	ds_read_b128 v[102:105], v8 offset:2048
	ds_read_b128 v[128:131], v8 offset:4096
	ds_read_b128 v[132:135], v8 offset:6144
	ds_read_b128 v[138:141], v9 offset:16384
	ds_read_b128 v[142:145], v9 offset:18432
	ds_read_b128 v[152:155], v9 offset:20480
	ds_read_b128 v[6:9], v9 offset:22528
	v_mfma_f32_16x16x32_bf16 v[84:87], v[112:115], v[66:69], v[84:87]
	v_mfma_f32_16x16x32_bf16 v[88:91], v[116:119], v[66:69], v[88:91]
	v_mfma_f32_16x16x32_bf16 v[92:95], v[120:123], v[66:69], v[92:95]
	v_mfma_f32_16x16x32_bf16 v[2:5], v[124:127], v[66:69], v[2:5]
	v_mfma_f32_16x16x32_bf16 v[20:23], v[112:115], v[72:75], v[22:25]
	v_mfma_f32_16x16x32_bf16 v[38:41], v[116:119], v[72:75], v[38:41]
	v_mfma_f32_16x16x32_bf16 v[46:49], v[120:123], v[72:75], v[46:49]
	v_mfma_f32_16x16x32_bf16 v[50:53], v[124:127], v[72:75], v[50:53]
	v_mfma_f32_16x16x32_bf16 v[42:45], v[112:115], v[76:79], v[42:45]
	v_mfma_f32_16x16x32_bf16 v[58:61], v[116:119], v[76:79], v[58:61]
	v_mfma_f32_16x16x32_bf16 v[62:65], v[120:123], v[76:79], v[62:65]
	v_mfma_f32_16x16x32_bf16 v[54:57], v[124:127], v[76:79], v[54:57]
	v_mfma_f32_16x16x32_bf16 v[34:37], v[112:115], v[106:109], v[34:37]
	v_mfma_f32_16x16x32_bf16 v[30:33], v[116:119], v[106:109], v[30:33]
	v_mfma_f32_16x16x32_bf16 v[24:27], v[120:123], v[106:109], v[26:29]
	v_mfma_f32_16x16x32_bf16 v[12:15], v[124:127], v[106:109], v[12:15]
	ds_read_b128 v[66:69], v10
	ds_read_b128 v[72:75], v10 offset:2048
	ds_read_b128 v[76:79], v10 offset:4096
	ds_read_b128 v[106:109], v10 offset:6144
	ds_read_b128 v[112:115], v11 offset:16384
	ds_read_b128 v[116:119], v11 offset:18432
	ds_read_b128 v[120:123], v11 offset:20480
	ds_read_b128 v[124:127], v11 offset:22528
	s_add_i32 s0, s0, 0xffff4d00
	s_waitcnt lgkmcnt(8)
	v_mfma_f32_16x16x32_bf16 v[84:87], v[138:141], v[16:19], v[84:87]
	v_mfma_f32_16x16x32_bf16 v[88:91], v[142:145], v[16:19], v[88:91]
	v_mfma_f32_16x16x32_bf16 v[92:95], v[152:155], v[16:19], v[92:95]
	v_mfma_f32_16x16x32_bf16 v[2:5], v[6:9], v[16:19], v[2:5]
	v_mfma_f32_16x16x32_bf16 v[16:19], v[138:141], v[102:105], v[20:23]
	v_mfma_f32_16x16x32_bf16 v[20:23], v[142:145], v[102:105], v[38:41]
	v_mfma_f32_16x16x32_bf16 v[38:41], v[152:155], v[102:105], v[46:49]
	v_mfma_f32_16x16x32_bf16 v[46:49], v[6:9], v[102:105], v[50:53]
	v_mfma_f32_16x16x32_bf16 v[42:45], v[138:141], v[128:131], v[42:45]
	v_mfma_f32_16x16x32_bf16 v[50:53], v[142:145], v[128:131], v[58:61]
	v_mfma_f32_16x16x32_bf16 v[58:61], v[152:155], v[128:131], v[62:65]
	v_mfma_f32_16x16x32_bf16 v[54:57], v[6:9], v[128:131], v[54:57]
	v_mfma_f32_16x16x32_bf16 v[34:37], v[138:141], v[132:135], v[34:37]
	v_mfma_f32_16x16x32_bf16 v[28:31], v[142:145], v[132:135], v[30:33]
	v_mfma_f32_16x16x32_bf16 v[24:27], v[152:155], v[132:135], v[24:27]
	v_mfma_f32_16x16x32_bf16 v[6:9], v[6:9], v[132:135], v[12:15]
	s_waitcnt vmcnt(0) lgkmcnt(0)
	s_barrier
	v_mfma_f32_16x16x32_bf16 v[10:13], v[112:115], v[66:69], v[84:87]
	v_mfma_f32_16x16x32_bf16 v[62:65], v[116:119], v[66:69], v[88:91]
	v_mfma_f32_16x16x32_bf16 v[84:87], v[120:123], v[66:69], v[92:95]
	v_mfma_f32_16x16x32_bf16 v[2:5], v[124:127], v[66:69], v[2:5]
	v_mfma_f32_16x16x32_bf16 v[14:17], v[112:115], v[72:75], v[16:19]
	v_mfma_f32_16x16x32_bf16 v[18:21], v[116:119], v[72:75], v[20:23]
	v_mfma_f32_16x16x32_bf16 v[38:41], v[120:123], v[72:75], v[38:41]
	v_mfma_f32_16x16x32_bf16 v[46:49], v[124:127], v[72:75], v[46:49]
	v_mfma_f32_16x16x32_bf16 v[42:45], v[112:115], v[76:79], v[42:45]
	v_mfma_f32_16x16x32_bf16 v[50:53], v[116:119], v[76:79], v[50:53]
	v_mfma_f32_16x16x32_bf16 v[58:61], v[120:123], v[76:79], v[58:61]
	v_mfma_f32_16x16x32_bf16 v[54:57], v[124:127], v[76:79], v[54:57]
	v_mfma_f32_16x16x32_bf16 v[32:35], v[112:115], v[106:109], v[34:37]
	v_mfma_f32_16x16x32_bf16 v[28:31], v[116:119], v[106:109], v[28:31]
	v_mfma_f32_16x16x32_bf16 v[22:25], v[120:123], v[106:109], v[24:27]
	v_mfma_f32_16x16x32_bf16 v[6:9], v[124:127], v[106:109], v[6:9]
	s_nop 1
	v_or_b32_e32 v26, s0, v101
	v_lshl_add_u32 v26, v82, 6, v26
	s_and_b32 s0, s58, 3
	v_mul_u32_u24_e32 v98, s0, v149
	v_ashrrev_i32_e32 v27, 31, v26
	v_lshl_add_u64 v[36:37], v[26:27], 0, v[98:99]
	v_mov_b64_e32 v[66:67], s[16:17]
	v_mad_u64_u32 v[68:69], s[0:1], v36, s70, v[66:67]
	v_mad_i32_i24 v69, v37, s70, v69
	s_mov_b64 s[8:9], 0x2000
	v_lshl_add_u64 v[36:37], v[68:69], 0, s[8:9]
	v_lshlrev_b32_e32 v68, 7, v83
	v_mov_b32_e32 v69, v99
	v_lshl_add_u64 v[72:73], v[36:37], 0, v[68:69]
	v_lshlrev_b32_e32 v74, 4, v110
	v_mov_b32_e32 v75, v99
	v_lshl_add_u64 v[72:73], v[72:73], 0, v[74:75]
	v_cvt_pk_bf16_f32 v10, v10, v11
	v_cvt_pk_bf16_f32 v11, v12, v13
	v_cvt_pk_bf16_f32 v12, v62, v63
	v_cvt_pk_bf16_f32 v13, v64, v65
	s_waitcnt lgkmcnt(0)
	s_barrier
	global_store_dwordx4 v[72:73], v[10:13], off
	s_nop 1
	v_cvt_pk_bf16_f32 v12, v2, v3
	v_or_b32_e32 v2, 16, v26
	v_ashrrev_i32_e32 v3, 31, v2
	v_lshl_add_u64 v[2:3], v[2:3], 0, v[98:99]
	v_lshl_add_u64 v[10:11], v[36:37], 0, v[74:75]
	v_or_b32_e32 v36, 64, v68
	v_mov_b32_e32 v37, v99
	v_cvt_pk_bf16_f32 v13, v4, v5
	v_mad_u64_u32 v[4:5], s[0:1], v2, s70, v[66:67]
	v_lshl_add_u64 v[62:63], v[10:11], 0, v[36:37]
	v_cvt_pk_bf16_f32 v10, v84, v85
	v_cvt_pk_bf16_f32 v11, v86, v87
	v_mad_i32_i24 v5, v3, s70, v5
	global_store_dwordx4 v[62:63], v[10:13], off
	s_nop 1
	v_lshl_add_u64 v[10:11], v[4:5], 0, s[8:9]
	v_lshl_add_u64 v[2:3], v[10:11], 0, v[68:69]
	v_lshl_add_u64 v[12:13], v[2:3], 0, v[74:75]
	v_cvt_pk_bf16_f32 v2, v14, v15
	v_cvt_pk_bf16_f32 v3, v16, v17
	v_cvt_pk_bf16_f32 v4, v18, v19
	v_cvt_pk_bf16_f32 v5, v20, v21
	global_store_dwordx4 v[12:13], v[2:5], off
	s_nop 1
	v_lshl_add_u64 v[2:3], v[10:11], 0, v[74:75]
	v_lshl_add_u64 v[10:11], v[2:3], 0, v[36:37]
	v_cvt_pk_bf16_f32 v2, v38, v39
	v_cvt_pk_bf16_f32 v3, v40, v41
	v_cvt_pk_bf16_f32 v4, v46, v47
	v_cvt_pk_bf16_f32 v5, v48, v49
	global_store_dwordx4 v[10:11], v[2:5], off
	s_nop 1
	v_or_b32_e32 v2, 32, v26
	v_ashrrev_i32_e32 v3, 31, v2
	v_lshl_add_u64 v[2:3], v[2:3], 0, v[98:99]
	v_mad_u64_u32 v[4:5], s[0:1], v2, s70, v[66:67]
	v_mad_i32_i24 v5, v3, s70, v5
	v_lshl_add_u64 v[10:11], v[4:5], 0, s[8:9]
	v_lshl_add_u64 v[2:3], v[10:11], 0, v[68:69]
	v_lshl_add_u64 v[12:13], v[2:3], 0, v[74:75]
	v_cvt_pk_bf16_f32 v2, v42, v43
	v_cvt_pk_bf16_f32 v3, v44, v45
	v_cvt_pk_bf16_f32 v4, v50, v51
	v_cvt_pk_bf16_f32 v5, v52, v53
	global_store_dwordx4 v[12:13], v[2:5], off
	s_nop 1
	v_lshl_add_u64 v[2:3], v[10:11], 0, v[74:75]
	v_lshl_add_u64 v[10:11], v[2:3], 0, v[36:37]
	v_cvt_pk_bf16_f32 v2, v58, v59
	v_cvt_pk_bf16_f32 v3, v60, v61
	v_cvt_pk_bf16_f32 v4, v54, v55
	v_cvt_pk_bf16_f32 v5, v56, v57
	global_store_dwordx4 v[10:11], v[2:5], off
	s_nop 1
	v_or_b32_e32 v2, 48, v26
	v_ashrrev_i32_e32 v3, 31, v2
	v_lshl_add_u64 v[2:3], v[2:3], 0, v[98:99]
	v_mad_u64_u32 v[4:5], s[0:1], v2, s70, v[66:67]
	v_mad_i32_i24 v5, v3, s70, v5
	v_lshl_add_u64 v[10:11], v[4:5], 0, s[8:9]
	v_lshl_add_u64 v[2:3], v[10:11], 0, v[68:69]
	v_lshl_add_u64 v[12:13], v[2:3], 0, v[74:75]
	v_cvt_pk_bf16_f32 v2, v32, v33
	v_cvt_pk_bf16_f32 v3, v34, v35
	v_cvt_pk_bf16_f32 v4, v28, v29
	v_cvt_pk_bf16_f32 v5, v30, v31
	global_store_dwordx4 v[12:13], v[2:5], off
	s_mov_b64 s[0:1], 0
	s_nop 0
	v_lshl_add_u64 v[2:3], v[10:11], 0, v[74:75]
	v_lshl_add_u64 v[10:11], v[2:3], 0, v[36:37]
	v_cvt_pk_bf16_f32 v2, v22, v23
	v_cvt_pk_bf16_f32 v3, v24, v25
	v_cvt_pk_bf16_f32 v4, v6, v7
	v_cvt_pk_bf16_f32 v5, v8, v9
	global_store_dwordx4 v[10:11], v[2:5], off

.Ldq_skip1:
	s_mov_b64 exec, s[8:9]
	s_mov_b32 s99, 1
	ds_read_b128 v[72:75], v16
	ds_read_b128 v[76:79], v16 offset:2048
	ds_read_b128 v[106:109], v16 offset:4096
	ds_read_b128 v[112:115], v16 offset:6144
	ds_read_b128 v[116:119], v17
	ds_read_b128 v[120:123], v17 offset:2048
	ds_read_b128 v[124:127], v17 offset:4096
	ds_read_b128 v[128:131], v17 offset:6144
	s_waitcnt lgkmcnt(8)
	v_mfma_f32_16x16x32_bf16 v[84:87], v[152:155], v[102:105], v[84:87]
	v_mfma_f32_16x16x32_bf16 v[88:91], v[156:159], v[102:105], v[88:91]
	v_mfma_f32_16x16x32_bf16 v[92:95], v[160:163], v[102:105], v[92:95]
	v_mfma_f32_16x16x32_bf16 v[22:25], v[164:167], v[102:105], v[22:25]
	v_mfma_f32_16x16x32_bf16 v[38:41], v[152:155], v[132:135], v[38:41]
	v_mfma_f32_16x16x32_bf16 v[46:49], v[156:159], v[132:135], v[46:49]
	v_mfma_f32_16x16x32_bf16 v[58:61], v[160:163], v[132:135], v[58:61]
	v_mfma_f32_16x16x32_bf16 v[50:53], v[164:167], v[132:135], v[50:53]
	v_mfma_f32_16x16x32_bf16 v[42:45], v[152:155], v[138:141], v[42:45]
	v_mfma_f32_16x16x32_bf16 v[62:65], v[156:159], v[138:141], v[62:65]
	v_mfma_f32_16x16x32_bf16 v[66:69], v[160:163], v[138:141], v[66:69]
	v_mfma_f32_16x16x32_bf16 v[54:57], v[164:167], v[138:141], v[54:57]
	v_mfma_f32_16x16x32_bf16 v[34:37], v[152:155], v[142:145], v[34:37]
	v_mfma_f32_16x16x32_bf16 v[30:33], v[156:159], v[142:145], v[30:33]
	v_mfma_f32_16x16x32_bf16 v[26:29], v[160:163], v[142:145], v[26:29]
	v_mfma_f32_16x16x32_bf16 v[18:21], v[164:167], v[142:145], v[18:21]
	s_waitcnt vmcnt(6) lgkmcnt(0)
	s_barrier
	ds_read_b128 v[102:105], v8
	ds_read_b128 v[132:135], v8 offset:2048
	ds_read_b128 v[138:141], v8 offset:4096
	ds_read_b128 v[142:145], v8 offset:6144
	ds_read_b128 v[152:155], v9 offset:16384
	ds_read_b128 v[156:159], v9 offset:18432
	ds_read_b128 v[160:163], v9 offset:20480
	ds_read_b128 v[164:167], v9 offset:22528
	v_mfma_f32_16x16x32_bf16 v[84:87], v[116:119], v[72:75], v[84:87]
	v_mfma_f32_16x16x32_bf16 v[88:91], v[120:123], v[72:75], v[88:91]
	v_mfma_f32_16x16x32_bf16 v[92:95], v[124:127], v[72:75], v[92:95]
	v_mfma_f32_16x16x32_bf16 v[22:25], v[128:131], v[72:75], v[22:25]
	v_mfma_f32_16x16x32_bf16 v[38:41], v[116:119], v[76:79], v[38:41]
	v_mfma_f32_16x16x32_bf16 v[46:49], v[120:123], v[76:79], v[46:49]
	v_mfma_f32_16x16x32_bf16 v[58:61], v[124:127], v[76:79], v[58:61]
	v_mfma_f32_16x16x32_bf16 v[50:53], v[128:131], v[76:79], v[50:53]
	v_mfma_f32_16x16x32_bf16 v[42:45], v[116:119], v[106:109], v[42:45]
	v_mfma_f32_16x16x32_bf16 v[62:65], v[120:123], v[106:109], v[62:65]
	v_mfma_f32_16x16x32_bf16 v[66:69], v[124:127], v[106:109], v[66:69]
	v_mfma_f32_16x16x32_bf16 v[54:57], v[128:131], v[106:109], v[54:57]
	v_mfma_f32_16x16x32_bf16 v[34:37], v[116:119], v[112:115], v[34:37]
	v_mfma_f32_16x16x32_bf16 v[30:33], v[120:123], v[112:115], v[30:33]
	v_mfma_f32_16x16x32_bf16 v[26:29], v[124:127], v[112:115], v[26:29]
	v_mfma_f32_16x16x32_bf16 v[18:21], v[128:131], v[112:115], v[18:21]
	s_mov_b64 s[8:9], 0x700
	s_mov_b32 m0, s64
	v_lshl_add_u64 v[72:73], v[2:3], 0, s[8:9]
	global_load_lds_dwordx4 v[72:73], off
	v_lshl_add_u64 v[72:73], v[4:5], 0, s[8:9]
	s_mov_b32 m0, s71
	s_nop 0
	global_load_lds_dwordx4 v[72:73], off
	v_lshl_add_u64 v[72:73], v[6:7], 0, s[8:9]
	s_mov_b32 m0, s73
	s_mov_b64 s[8:9], 0x20700
	global_load_lds_dwordx4 v[72:73], off
	v_lshl_add_u64 v[72:73], v[6:7], 0, s[8:9]
	s_mov_b32 m0, s74
	s_mov_b64 s[8:9], 0x40700
	global_load_lds_dwordx4 v[72:73], off
	v_lshl_add_u64 v[72:73], v[6:7], 0, s[8:9]
	s_mov_b32 m0, s75
	s_mov_b64 s[8:9], 0x60700
	global_load_lds_dwordx4 v[72:73], off
	v_lshl_add_u64 v[72:73], v[6:7], 0, s[8:9]
	s_mov_b32 m0, s76
	s_nop 0
	global_load_lds_dwordx4 v[72:73], off
	ds_read_b128 v[72:75], v10
	ds_read_b128 v[76:79], v10 offset:2048
	ds_read_b128 v[106:109], v10 offset:4096
	ds_read_b128 v[112:115], v10 offset:6144
	ds_read_b128 v[116:119], v11 offset:16384
	ds_read_b128 v[120:123], v11 offset:18432
	ds_read_b128 v[124:127], v11 offset:20480
	ds_read_b128 v[128:131], v11 offset:22528
	s_waitcnt lgkmcnt(8)
	v_mfma_f32_16x16x32_bf16 v[84:87], v[152:155], v[102:105], v[84:87]
	v_mfma_f32_16x16x32_bf16 v[88:91], v[156:159], v[102:105], v[88:91]
	v_mfma_f32_16x16x32_bf16 v[92:95], v[160:163], v[102:105], v[92:95]
	v_mfma_f32_16x16x32_bf16 v[22:25], v[164:167], v[102:105], v[22:25]
	v_mfma_f32_16x16x32_bf16 v[38:41], v[152:155], v[132:135], v[38:41]
	v_mfma_f32_16x16x32_bf16 v[46:49], v[156:159], v[132:135], v[46:49]
	v_mfma_f32_16x16x32_bf16 v[58:61], v[160:163], v[132:135], v[58:61]
	v_mfma_f32_16x16x32_bf16 v[50:53], v[164:167], v[132:135], v[50:53]
	v_mfma_f32_16x16x32_bf16 v[42:45], v[152:155], v[138:141], v[42:45]
	v_mfma_f32_16x16x32_bf16 v[62:65], v[156:159], v[138:141], v[62:65]
	v_mfma_f32_16x16x32_bf16 v[66:69], v[160:163], v[138:141], v[66:69]
	v_mfma_f32_16x16x32_bf16 v[54:57], v[164:167], v[138:141], v[54:57]
	v_mfma_f32_16x16x32_bf16 v[34:37], v[152:155], v[142:145], v[34:37]
	v_mfma_f32_16x16x32_bf16 v[30:33], v[156:159], v[142:145], v[30:33]
	v_mfma_f32_16x16x32_bf16 v[26:29], v[160:163], v[142:145], v[26:29]
	v_mfma_f32_16x16x32_bf16 v[18:21], v[164:167], v[142:145], v[18:21]
	s_waitcnt vmcnt(6) lgkmcnt(0)
	s_barrier
	ds_read_b128 v[102:105], v8 offset:49152
	ds_read_b128 v[132:135], v8 offset:51200
	ds_read_b128 v[138:141], v8 offset:53248
	ds_read_b128 v[142:145], v8 offset:55296
	ds_read_b128 v[152:155], v12
	ds_read_b128 v[156:159], v12 offset:2048
	ds_read_b128 v[160:163], v12 offset:4096
	ds_read_b128 v[164:167], v12 offset:6144
	v_mfma_f32_16x16x32_bf16 v[84:87], v[116:119], v[72:75], v[84:87]
	v_mfma_f32_16x16x32_bf16 v[88:91], v[120:123], v[72:75], v[88:91]
	v_mfma_f32_16x16x32_bf16 v[92:95], v[124:127], v[72:75], v[92:95]
	v_mfma_f32_16x16x32_bf16 v[22:25], v[128:131], v[72:75], v[22:25]
	v_mfma_f32_16x16x32_bf16 v[38:41], v[116:119], v[76:79], v[38:41]
	v_mfma_f32_16x16x32_bf16 v[46:49], v[120:123], v[76:79], v[46:49]
	v_mfma_f32_16x16x32_bf16 v[58:61], v[124:127], v[76:79], v[58:61]
	v_mfma_f32_16x16x32_bf16 v[50:53], v[128:131], v[76:79], v[50:53]
	v_mfma_f32_16x16x32_bf16 v[42:45], v[116:119], v[106:109], v[42:45]
	v_mfma_f32_16x16x32_bf16 v[62:65], v[120:123], v[106:109], v[62:65]
	v_mfma_f32_16x16x32_bf16 v[66:69], v[124:127], v[106:109], v[66:69]
	v_mfma_f32_16x16x32_bf16 v[54:57], v[128:131], v[106:109], v[54:57]
	v_mfma_f32_16x16x32_bf16 v[34:37], v[116:119], v[112:115], v[34:37]
	v_mfma_f32_16x16x32_bf16 v[30:33], v[120:123], v[112:115], v[30:33]
	v_mfma_f32_16x16x32_bf16 v[26:29], v[124:127], v[112:115], v[26:29]
	v_mfma_f32_16x16x32_bf16 v[18:21], v[128:131], v[112:115], v[18:21]
	s_mov_b64 s[8:9], 0x780
	s_mov_b32 m0, s57
	v_lshl_add_u64 v[2:3], v[2:3], 0, s[8:9]
	global_load_lds_dwordx4 v[2:3], off
	v_lshl_add_u64 v[2:3], v[4:5], 0, s[8:9]
	s_mov_b32 m0, s5
	s_nop 0
	global_load_lds_dwordx4 v[2:3], off
	v_lshl_add_u64 v[2:3], v[6:7], 0, s[8:9]
	s_mov_b32 m0, s33
	s_mov_b64 s[8:9], 0x20780
	global_load_lds_dwordx4 v[2:3], off
	v_lshl_add_u64 v[2:3], v[6:7], 0, s[8:9]
	s_mov_b32 m0, s38
	s_mov_b64 s[8:9], 0x40780
	global_load_lds_dwordx4 v[2:3], off
	v_lshl_add_u64 v[2:3], v[6:7], 0, s[8:9]
	s_mov_b32 m0, s39
	s_mov_b64 s[8:9], 0x60780
	global_load_lds_dwordx4 v[2:3], off
	v_lshl_add_u64 v[2:3], v[6:7], 0, s[8:9]
	s_mov_b32 m0, s56
	s_nop 0
	global_load_lds_dwordx4 v[2:3], off
	ds_read_b128 v[2:5], v10 offset:49152
	ds_read_b128 v[72:75], v10 offset:51200
	ds_read_b128 v[76:79], v10 offset:53248
	ds_read_b128 v[106:109], v10 offset:55296
	ds_read_b128 v[112:115], v13
	ds_read_b128 v[116:119], v13 offset:2048
	ds_read_b128 v[120:123], v13 offset:4096
	ds_read_b128 v[124:127], v13 offset:6144
	s_waitcnt lgkmcnt(8)
	v_mfma_f32_16x16x32_bf16 v[84:87], v[152:155], v[102:105], v[84:87]
	v_mfma_f32_16x16x32_bf16 v[88:91], v[156:159], v[102:105], v[88:91]
	v_mfma_f32_16x16x32_bf16 v[92:95], v[160:163], v[102:105], v[92:95]
	v_mfma_f32_16x16x32_bf16 v[22:25], v[164:167], v[102:105], v[22:25]
	v_mfma_f32_16x16x32_bf16 v[38:41], v[152:155], v[132:135], v[38:41]
	v_mfma_f32_16x16x32_bf16 v[46:49], v[156:159], v[132:135], v[46:49]
	v_mfma_f32_16x16x32_bf16 v[58:61], v[160:163], v[132:135], v[58:61]
	v_mfma_f32_16x16x32_bf16 v[50:53], v[164:167], v[132:135], v[50:53]
	v_mfma_f32_16x16x32_bf16 v[42:45], v[152:155], v[138:141], v[42:45]
	v_mfma_f32_16x16x32_bf16 v[62:65], v[156:159], v[138:141], v[62:65]
	v_mfma_f32_16x16x32_bf16 v[66:69], v[160:163], v[138:141], v[66:69]
	v_mfma_f32_16x16x32_bf16 v[54:57], v[164:167], v[138:141], v[54:57]
	v_mfma_f32_16x16x32_bf16 v[34:37], v[152:155], v[142:145], v[34:37]
	v_mfma_f32_16x16x32_bf16 v[30:33], v[156:159], v[142:145], v[30:33]
	v_mfma_f32_16x16x32_bf16 v[26:29], v[160:163], v[142:145], v[26:29]
	v_mfma_f32_16x16x32_bf16 v[18:21], v[164:167], v[142:145], v[18:21]
	s_waitcnt vmcnt(6) lgkmcnt(0)
	s_barrier
	ds_read_b128 v[102:105], v14
	ds_read_b128 v[128:131], v14 offset:2048
	ds_read_b128 v[132:135], v14 offset:4096
	ds_read_b128 v[138:141], v14 offset:6144
	ds_read_b128 v[142:145], v15
	ds_read_b128 v[152:155], v15 offset:2048
	ds_read_b128 v[156:159], v15 offset:4096
	ds_read_b128 v[12:15], v15 offset:6144
	v_mfma_f32_16x16x32_bf16 v[84:87], v[112:115], v[2:5], v[84:87]
	v_mfma_f32_16x16x32_bf16 v[88:91], v[116:119], v[2:5], v[88:91]
	v_mfma_f32_16x16x32_bf16 v[92:95], v[120:123], v[2:5], v[92:95]
	v_mfma_f32_16x16x32_bf16 v[2:5], v[124:127], v[2:5], v[22:25]
	v_mfma_f32_16x16x32_bf16 v[22:25], v[112:115], v[72:75], v[38:41]
	v_mfma_f32_16x16x32_bf16 v[38:41], v[116:119], v[72:75], v[46:49]
	v_mfma_f32_16x16x32_bf16 v[46:49], v[120:123], v[72:75], v[58:61]
	v_mfma_f32_16x16x32_bf16 v[50:53], v[124:127], v[72:75], v[50:53]
	v_mfma_f32_16x16x32_bf16 v[42:45], v[112:115], v[76:79], v[42:45]
	v_mfma_f32_16x16x32_bf16 v[58:61], v[116:119], v[76:79], v[62:65]
	v_mfma_f32_16x16x32_bf16 v[62:65], v[120:123], v[76:79], v[66:69]
	v_mfma_f32_16x16x32_bf16 v[54:57], v[124:127], v[76:79], v[54:57]
	v_mfma_f32_16x16x32_bf16 v[34:37], v[112:115], v[106:109], v[34:37]
	v_mfma_f32_16x16x32_bf16 v[30:33], v[116:119], v[106:109], v[30:33]
	v_mfma_f32_16x16x32_bf16 v[26:29], v[120:123], v[106:109], v[26:29]
	v_mfma_f32_16x16x32_bf16 v[18:21], v[124:127], v[106:109], v[18:21]
	ds_read_b128 v[66:69], v16
	ds_read_b128 v[72:75], v16 offset:2048
	ds_read_b128 v[76:79], v16 offset:4096
	ds_read_b128 v[106:109], v16 offset:6144
	ds_read_b128 v[112:115], v17
	ds_read_b128 v[116:119], v17 offset:2048
	ds_read_b128 v[120:123], v17 offset:4096
	ds_read_b128 v[124:127], v17 offset:6144
	s_waitcnt lgkmcnt(8)
	v_mfma_f32_16x16x32_bf16 v[84:87], v[142:145], v[102:105], v[84:87]
	v_mfma_f32_16x16x32_bf16 v[88:91], v[152:155], v[102:105], v[88:91]
	v_mfma_f32_16x16x32_bf16 v[92:95], v[156:159], v[102:105], v[92:95]
	v_mfma_f32_16x16x32_bf16 v[2:5], v[12:15], v[102:105], v[2:5]
	v_mfma_f32_16x16x32_bf16 v[22:25], v[142:145], v[128:131], v[22:25]
	v_mfma_f32_16x16x32_bf16 v[38:41], v[152:155], v[128:131], v[38:41]
	v_mfma_f32_16x16x32_bf16 v[46:49], v[156:159], v[128:131], v[46:49]
	v_mfma_f32_16x16x32_bf16 v[50:53], v[12:15], v[128:131], v[50:53]
	v_mfma_f32_16x16x32_bf16 v[42:45], v[142:145], v[132:135], v[42:45]
	v_mfma_f32_16x16x32_bf16 v[58:61], v[152:155], v[132:135], v[58:61]
	v_mfma_f32_16x16x32_bf16 v[62:65], v[156:159], v[132:135], v[62:65]
	v_mfma_f32_16x16x32_bf16 v[54:57], v[12:15], v[132:135], v[54:57]
	v_mfma_f32_16x16x32_bf16 v[34:37], v[142:145], v[138:141], v[34:37]
	v_mfma_f32_16x16x32_bf16 v[30:33], v[152:155], v[138:141], v[30:33]
	v_mfma_f32_16x16x32_bf16 v[26:29], v[156:159], v[138:141], v[26:29]
	v_mfma_f32_16x16x32_bf16 v[12:15], v[12:15], v[138:141], v[18:21]
	s_waitcnt vmcnt(0) lgkmcnt(0)
	s_barrier
	s_mov_b64 s[20:21], exec
	v_readlane_b32 s22, v197, 0
	v_readlane_b32 s23, v197, 1
	s_and_b64 s[22:23], s[20:21], s[22:23]
	s_mov_b64 exec, s[22:23]
	s_cbranch_execz .Ldq_pskip1
	v_mov_b32_e32 v253, 0x24008
	ds_write_b32 v253, v250
.Ldq_pskip1:
	s_mov_b64 exec, s[20:21]
	s_nop 1
	ds_read_b128 v[16:19], v8
	ds_read_b128 v[102:105], v8 offset:2048
	ds_read_b128 v[128:131], v8 offset:4096
	ds_read_b128 v[132:135], v8 offset:6144
	ds_read_b128 v[138:141], v9 offset:16384
	ds_read_b128 v[142:145], v9 offset:18432
	ds_read_b128 v[152:155], v9 offset:20480
	ds_read_b128 v[6:9], v9 offset:22528
	v_mfma_f32_16x16x32_bf16 v[84:87], v[112:115], v[66:69], v[84:87]
	v_mfma_f32_16x16x32_bf16 v[88:91], v[116:119], v[66:69], v[88:91]
	v_mfma_f32_16x16x32_bf16 v[92:95], v[120:123], v[66:69], v[92:95]
	v_mfma_f32_16x16x32_bf16 v[2:5], v[124:127], v[66:69], v[2:5]
	v_mfma_f32_16x16x32_bf16 v[20:23], v[112:115], v[72:75], v[22:25]
	v_mfma_f32_16x16x32_bf16 v[38:41], v[116:119], v[72:75], v[38:41]
	v_mfma_f32_16x16x32_bf16 v[46:49], v[120:123], v[72:75], v[46:49]
	v_mfma_f32_16x16x32_bf16 v[50:53], v[124:127], v[72:75], v[50:53]
	v_mfma_f32_16x16x32_bf16 v[42:45], v[112:115], v[76:79], v[42:45]
	v_mfma_f32_16x16x32_bf16 v[58:61], v[116:119], v[76:79], v[58:61]
	v_mfma_f32_16x16x32_bf16 v[62:65], v[120:123], v[76:79], v[62:65]
	v_mfma_f32_16x16x32_bf16 v[54:57], v[124:127], v[76:79], v[54:57]
	v_mfma_f32_16x16x32_bf16 v[34:37], v[112:115], v[106:109], v[34:37]
	v_mfma_f32_16x16x32_bf16 v[30:33], v[116:119], v[106:109], v[30:33]
	v_mfma_f32_16x16x32_bf16 v[24:27], v[120:123], v[106:109], v[26:29]
	v_mfma_f32_16x16x32_bf16 v[12:15], v[124:127], v[106:109], v[12:15]
	ds_read_b128 v[66:69], v10
	ds_read_b128 v[72:75], v10 offset:2048
	ds_read_b128 v[76:79], v10 offset:4096
	ds_read_b128 v[106:109], v10 offset:6144
	ds_read_b128 v[112:115], v11 offset:16384
	ds_read_b128 v[116:119], v11 offset:18432
	ds_read_b128 v[120:123], v11 offset:20480
	ds_read_b128 v[124:127], v11 offset:22528
	s_waitcnt lgkmcnt(8)
	v_mfma_f32_16x16x32_bf16 v[84:87], v[138:141], v[16:19], v[84:87]
	v_mfma_f32_16x16x32_bf16 v[88:91], v[142:145], v[16:19], v[88:91]
	v_mfma_f32_16x16x32_bf16 v[92:95], v[152:155], v[16:19], v[92:95]
	v_mfma_f32_16x16x32_bf16 v[2:5], v[6:9], v[16:19], v[2:5]
	v_mfma_f32_16x16x32_bf16 v[16:19], v[138:141], v[102:105], v[20:23]
	v_mfma_f32_16x16x32_bf16 v[20:23], v[142:145], v[102:105], v[38:41]
	v_mfma_f32_16x16x32_bf16 v[38:41], v[152:155], v[102:105], v[46:49]
	v_mfma_f32_16x16x32_bf16 v[46:49], v[6:9], v[102:105], v[50:53]
	v_mfma_f32_16x16x32_bf16 v[42:45], v[138:141], v[128:131], v[42:45]
	v_mfma_f32_16x16x32_bf16 v[102:105], v[142:145], v[128:131], v[58:61]
	v_mfma_f32_16x16x32_bf16 v[156:159], v[152:155], v[128:131], v[62:65]
	v_mfma_f32_16x16x32_bf16 v[128:131], v[6:9], v[128:131], v[54:57]
	v_mfma_f32_16x16x32_bf16 v[34:37], v[138:141], v[132:135], v[34:37]
	v_mfma_f32_16x16x32_bf16 v[138:141], v[142:145], v[132:135], v[30:33]
	v_mfma_f32_16x16x32_bf16 v[24:27], v[152:155], v[132:135], v[24:27]
	v_mfma_f32_16x16x32_bf16 v[132:135], v[6:9], v[132:135], v[12:15]
	s_waitcnt vmcnt(0) lgkmcnt(0)
	s_barrier
	v_mfma_f32_16x16x32_bf16 v[84:87], v[112:115], v[66:69], v[84:87]
	v_mfma_f32_16x16x32_bf16 v[88:91], v[116:119], v[66:69], v[88:91]
	v_mfma_f32_16x16x32_bf16 v[92:95], v[120:123], v[66:69], v[92:95]
	v_mfma_f32_16x16x32_bf16 v[142:145], v[124:127], v[66:69], v[2:5]
	v_mfma_f32_16x16x32_bf16 v[62:65], v[112:115], v[72:75], v[16:19]
	v_mfma_f32_16x16x32_bf16 v[58:61], v[116:119], v[72:75], v[20:23]
	v_mfma_f32_16x16x32_bf16 v[54:57], v[120:123], v[72:75], v[38:41]
	v_mfma_f32_16x16x32_bf16 v[50:53], v[124:127], v[72:75], v[46:49]
	v_mfma_f32_16x16x32_bf16 v[46:49], v[112:115], v[76:79], v[42:45]
	v_mfma_f32_16x16x32_bf16 v[42:45], v[116:119], v[76:79], v[102:105]
	v_mfma_f32_16x16x32_bf16 v[38:41], v[120:123], v[76:79], v[156:159]
	v_mfma_f32_16x16x32_bf16 v[30:33], v[124:127], v[76:79], v[128:131]
	v_mfma_f32_16x16x32_bf16 v[14:17], v[112:115], v[106:109], v[34:37]
	v_mfma_f32_16x16x32_bf16 v[10:13], v[116:119], v[106:109], v[138:141]
	v_mfma_f32_16x16x32_bf16 v[6:9], v[120:123], v[106:109], v[24:27]
	v_mfma_f32_16x16x32_bf16 v[2:5], v[124:127], v[106:109], v[132:135]
	v_readlane_b32 s72, v197, 2
	s_waitcnt lgkmcnt(0)
	s_barrier
	v_lshlrev_b32_e32 v18, 4, v110
	v_readlane_b32 s76, v197, 6
	v_readlane_b32 s77, v197, 7
	s_nop 4
	global_load_dwordx4 v[34:37], v18, s[76:77]
	global_load_dwordx4 v[26:29], v18, s[76:77] offset:64
	global_load_dwordx4 v[22:25], v18, s[76:77] offset:128
	s_nop 0
	global_load_dwordx4 v[18:21], v18, s[76:77] offset:192
	v_lshl_add_u32 v66, v82, 6, s1
	v_and_b32_e32 v67, 64, v150
	v_lshrrev_b32_e32 v68, 8, v66
	v_and_b32_e32 v80, 0xc0, v66
	v_xor_b32_e32 v66, 16, v150
	v_add_u32_e32 v67, 64, v67
	v_cmp_lt_i32_e32 vcc, v66, v67
	v_mov_b32_e32 v72, v85
	v_mov_b32_e32 v73, v89
	v_cndmask_b32_e32 v66, v150, v66, vcc
	v_lshlrev_b32_e32 v96, 2, v66
	v_xor_b32_e32 v66, 32, v150
	v_cmp_lt_i32_e32 vcc, v66, v67
	v_mul_hi_i32_i24_e32 v67, 0x1100, v68
	v_mov_b32_e32 v69, v88
	v_cndmask_b32_e32 v66, v150, v66, vcc
	v_lshlrev_b32_e32 v97, 2, v66
	v_mul_i32_i24_e32 v66, 0x1100, v68
	v_mov_b32_e32 v68, v84
	v_pk_mul_f32 v[72:73], v[72:73], v[72:73]
	v_mov_b32_e32 v74, v93
	v_pk_fma_f32 v[68:69], v[68:69], v[68:69], v[72:73]
	v_mov_b32_e32 v72, v86
	v_mov_b32_e32 v73, v90
	v_pk_fma_f32 v[68:69], v[72:73], v[72:73], v[68:69]
	v_mov_b32_e32 v72, v87
	v_mov_b32_e32 v73, v91
	v_mov_b32_e32 v75, v143
	v_pk_fma_f32 v[68:69], v[72:73], v[72:73], v[68:69]
	v_mov_b32_e32 v72, v92
	v_mov_b32_e32 v73, v142
	v_pk_mul_f32 v[74:75], v[74:75], v[74:75]
	v_mov_b32_e32 v76, v63
	v_pk_fma_f32 v[72:73], v[72:73], v[72:73], v[74:75]
	v_mov_b32_e32 v74, v94
	v_mov_b32_e32 v75, v144
	v_pk_fma_f32 v[72:73], v[74:75], v[74:75], v[72:73]
	v_mov_b32_e32 v74, v95
	v_mov_b32_e32 v75, v145
	v_mov_b32_e32 v77, v59
	v_pk_fma_f32 v[72:73], v[74:75], v[74:75], v[72:73]
	v_mov_b32_e32 v74, v62
	v_mov_b32_e32 v75, v58
	v_pk_mul_f32 v[76:77], v[76:77], v[76:77]
	v_mov_b32_e32 v78, v55
	v_pk_fma_f32 v[74:75], v[74:75], v[74:75], v[76:77]
	v_mov_b32_e32 v76, v64
	v_mov_b32_e32 v77, v60
	v_pk_fma_f32 v[74:75], v[76:77], v[76:77], v[74:75]
	v_mov_b32_e32 v76, v65
	v_mov_b32_e32 v77, v61
	v_mov_b32_e32 v79, v51
	v_pk_fma_f32 v[74:75], v[76:77], v[76:77], v[74:75]
	v_mov_b32_e32 v76, v54
	v_mov_b32_e32 v77, v50
	v_pk_mul_f32 v[78:79], v[78:79], v[78:79]
	s_lshl_b32 s0, s0, 9
	v_pk_fma_f32 v[76:77], v[76:77], v[76:77], v[78:79]
	v_mov_b32_e32 v78, v56
	v_mov_b32_e32 v79, v52
	v_pk_fma_f32 v[76:77], v[78:79], v[78:79], v[76:77]
	v_mov_b32_e32 v78, v57
	v_mov_b32_e32 v79, v53
	v_pk_fma_f32 v[76:77], v[78:79], v[78:79], v[76:77]
	v_mov_b32_e32 v78, v74
	v_mov_b32_e32 v79, v68
	v_mov_b32_e32 v68, v75
	v_pk_add_f32 v[68:69], v[78:79], v[68:69]
	v_mov_b32_e32 v74, v76
	v_mov_b32_e32 v75, v72
	v_pk_add_f32 v[68:69], v[68:69], v[74:75]
	v_mov_b32_e32 v72, v77
	v_pk_add_f32 v[68:69], v[68:69], v[72:73]
	ds_bpermute_b32 v73, v96, v69
	ds_bpermute_b32 v72, v96, v68
	v_lshl_or_b32 v98, v83, 7, s0
	s_mov_b32 s0, 0x358637bd
	v_readlane_b32 s83, v197, 13
	s_mov_b32 s8, 0x3c800000
	s_waitcnt lgkmcnt(0)
	v_pk_add_f32 v[68:69], v[68:69], v[72:73]
	ds_bpermute_b32 v73, v97, v69
	ds_bpermute_b32 v72, v97, v68
	s_mov_b32 s83, 0x800000
	v_readlane_b32 s82, v197, 12
	s_mov_b64 s[38:39], 0x1000
	s_movk_i32 s82, 0x600
	s_waitcnt lgkmcnt(0)
	v_pk_add_f32 v[68:69], v[68:69], v[72:73]
	v_mov_b64_e32 v[72:73], s[0:1]
	v_pk_fma_f32 v[76:77], v[68:69], s[8:9], v[72:73] op_sel_hi:[1,0,0]
	v_lshl_add_u64 v[66:67], v[66:67], 0, s[38:39]
	v_mul_f32_e32 v68, 0x4b800000, v77
	v_cmp_gt_f32_e32 vcc, s83, v77
	v_mul_lo_u32 v100, v67, s82
	v_or3_b32 v102, v80, v101, v66
	v_cndmask_b32_e32 v68, v77, v68, vcc
	v_rsq_f32_e32 v77, v68
	v_mov_b64_e32 v[66:67], s[14:15]
	v_mad_u64_u32 v[74:75], s[38:39], v102, s82, v[66:67]
	v_mul_f32_e32 v78, 0x45800000, v77
	v_cndmask_b32_e32 v78, v77, v78, vcc
	v_add_u32_e32 v75, v100, v75
	v_pk_mul_f32 v[80:81], v[84:85], v[78:79] op_sel_hi:[1,0]
	v_pk_mul_f32 v[84:85], v[86:87], v[78:79] op_sel_hi:[1,0]
	v_lshl_add_u64 v[74:75], v[74:75], 0, v[98:99]
	v_lshlrev_b32_e32 v68, 3, v110
	v_mov_b32_e32 v69, v99
	s_waitcnt vmcnt(0)
	v_pk_mul_f32 v[84:85], v[36:37], v[84:85]
	v_pk_mul_f32 v[80:81], v[34:35], v[80:81]
	v_lshl_add_u64 v[74:75], v[74:75], 0, v[68:69]
	v_cvt_pk_bf16_f32 v80, v80, v81
	v_cvt_pk_bf16_f32 v81, v84, v85
	global_store_dwordx2 v[74:75], v[80:81], off
	v_pk_mul_f32 v[80:81], v[88:89], v[78:79] op_sel_hi:[1,0]
	v_pk_mul_f32 v[84:85], v[90:91], v[78:79] op_sel_hi:[1,0]
	v_pk_mul_f32 v[80:81], v[26:27], v[80:81]
	v_pk_mul_f32 v[84:85], v[28:29], v[84:85]
	v_cvt_pk_bf16_f32 v80, v80, v81
	v_cvt_pk_bf16_f32 v81, v84, v85
	global_store_dwordx2 v[74:75], v[80:81], off offset:32
	v_pk_mul_f32 v[80:81], v[92:93], v[78:79] op_sel_hi:[1,0]
	v_pk_mul_f32 v[84:85], v[94:95], v[78:79] op_sel_hi:[1,0]
	v_mul_f32_e32 v77, 0x4b800000, v76
	v_cmp_gt_f32_e32 vcc, s83, v76
	v_pk_mul_f32 v[84:85], v[24:25], v[84:85]
	v_pk_mul_f32 v[80:81], v[22:23], v[80:81]
	v_cndmask_b32_e32 v76, v76, v77, vcc
	v_cvt_pk_bf16_f32 v80, v80, v81
	v_cvt_pk_bf16_f32 v81, v84, v85
	v_rsq_f32_e32 v84, v76
	global_store_dwordx2 v[74:75], v[80:81], off offset:64
	v_pk_mul_f32 v[80:81], v[142:143], v[78:79] op_sel_hi:[1,0]
	v_pk_mul_f32 v[78:79], v[144:145], v[78:79] op_sel_hi:[1,0]
	v_pk_mul_f32 v[80:81], v[18:19], v[80:81]
	v_pk_mul_f32 v[78:79], v[20:21], v[78:79]
	v_cvt_pk_bf16_f32 v76, v80, v81
	v_cvt_pk_bf16_f32 v77, v78, v79
	global_store_dwordx2 v[74:75], v[76:77], off offset:96
	v_mul_f32_e32 v74, 0x45800000, v84
	v_or_b32_e32 v75, 16, v102
	v_cndmask_b32_e32 v74, v84, v74, vcc
	v_mad_u64_u32 v[76:77], s[0:1], v75, s82, v[66:67]
	v_add_u32_e32 v77, v100, v77
	v_pk_mul_f32 v[54:55], v[54:55], v[74:75] op_sel_hi:[1,0]
	v_pk_mul_f32 v[56:57], v[56:57], v[74:75] op_sel_hi:[1,0]
	v_lshl_add_u64 v[76:77], v[76:77], 0, v[98:99]
	v_pk_mul_f32 v[56:57], v[24:25], v[56:57]
	v_pk_mul_f32 v[54:55], v[22:23], v[54:55]
	v_lshl_add_u64 v[76:77], v[76:77], 0, v[68:69]
	v_pk_mul_f32 v[58:59], v[58:59], v[74:75] op_sel_hi:[1,0]
	v_pk_mul_f32 v[60:61], v[60:61], v[74:75] op_sel_hi:[1,0]
	v_cvt_pk_bf16_f32 v54, v54, v55
	v_cvt_pk_bf16_f32 v55, v56, v57
	v_mov_b32_e32 v56, v47
	v_mov_b32_e32 v57, v43
	v_pk_mul_f32 v[60:61], v[28:29], v[60:61]
	v_pk_mul_f32 v[58:59], v[26:27], v[58:59]
	global_store_dwordx2 v[76:77], v[54:55], off offset:64
	v_mov_b32_e32 v54, v46
	v_mov_b32_e32 v55, v42
	v_pk_mul_f32 v[56:57], v[56:57], v[56:57]
	v_cvt_pk_bf16_f32 v58, v58, v59
	v_cvt_pk_bf16_f32 v59, v60, v61
	v_pk_fma_f32 v[54:55], v[54:55], v[54:55], v[56:57]
	v_mov_b32_e32 v56, v48
	v_mov_b32_e32 v57, v44
	global_store_dwordx2 v[76:77], v[58:59], off offset:32
	v_pk_fma_f32 v[54:55], v[56:57], v[56:57], v[54:55]
	v_mov_b32_e32 v56, v49
	v_mov_b32_e32 v57, v45
	v_mov_b32_e32 v58, v39
	v_mov_b32_e32 v59, v31
	v_pk_fma_f32 v[54:55], v[56:57], v[56:57], v[54:55]
	v_mov_b32_e32 v56, v38
	v_mov_b32_e32 v57, v30
	v_pk_mul_f32 v[58:59], v[58:59], v[58:59]
	v_pk_mul_f32 v[62:63], v[62:63], v[74:75] op_sel_hi:[1,0]
	v_pk_fma_f32 v[56:57], v[56:57], v[56:57], v[58:59]
	v_mov_b32_e32 v58, v40
	v_mov_b32_e32 v59, v32
	v_pk_mul_f32 v[64:65], v[64:65], v[74:75] op_sel_hi:[1,0]
	v_pk_fma_f32 v[56:57], v[58:59], v[58:59], v[56:57]
	v_mov_b32_e32 v58, v41
	v_mov_b32_e32 v59, v33
	v_mov_b32_e32 v60, v15
	v_mov_b32_e32 v61, v11
	v_pk_mul_f32 v[64:65], v[36:37], v[64:65]
	v_pk_mul_f32 v[62:63], v[34:35], v[62:63]
	v_pk_fma_f32 v[56:57], v[58:59], v[58:59], v[56:57]
	v_mov_b32_e32 v58, v14
	v_mov_b32_e32 v59, v10
	v_pk_mul_f32 v[60:61], v[60:61], v[60:61]
	v_cvt_pk_bf16_f32 v62, v62, v63
	v_cvt_pk_bf16_f32 v63, v64, v65
	v_pk_fma_f32 v[58:59], v[58:59], v[58:59], v[60:61]
	v_mov_b32_e32 v60, v16
	v_mov_b32_e32 v61, v12
	global_store_dwordx2 v[76:77], v[62:63], off
	v_pk_fma_f32 v[58:59], v[60:61], v[60:61], v[58:59]
	v_mov_b32_e32 v60, v17
	v_mov_b32_e32 v61, v13
	v_mov_b32_e32 v62, v7
	v_mov_b32_e32 v63, v3
	v_pk_fma_f32 v[58:59], v[60:61], v[60:61], v[58:59]
	v_mov_b32_e32 v60, v6
	v_mov_b32_e32 v61, v2
	v_pk_mul_f32 v[62:63], v[62:63], v[62:63]
	v_pk_mul_f32 v[50:51], v[50:51], v[74:75] op_sel_hi:[1,0]
	v_pk_fma_f32 v[60:61], v[60:61], v[60:61], v[62:63]
	v_mov_b32_e32 v62, v8
	v_mov_b32_e32 v63, v4
	v_pk_fma_f32 v[60:61], v[62:63], v[62:63], v[60:61]
	v_mov_b32_e32 v62, v9
	v_mov_b32_e32 v63, v5
	v_pk_fma_f32 v[60:61], v[62:63], v[62:63], v[60:61]
	v_mov_b32_e32 v62, v58
	v_mov_b32_e32 v63, v54
	v_mov_b32_e32 v54, v59
	v_pk_add_f32 v[54:55], v[62:63], v[54:55]
	v_mov_b32_e32 v58, v60
	v_mov_b32_e32 v59, v56
	v_pk_add_f32 v[54:55], v[54:55], v[58:59]
	v_mov_b32_e32 v56, v61
	v_pk_add_f32 v[54:55], v[54:55], v[56:57]
	ds_bpermute_b32 v57, v96, v55
	ds_bpermute_b32 v56, v96, v54
	v_pk_mul_f32 v[52:53], v[52:53], v[74:75] op_sel_hi:[1,0]
	v_pk_mul_f32 v[50:51], v[18:19], v[50:51]
	v_pk_mul_f32 v[52:53], v[20:21], v[52:53]
	v_cvt_pk_bf16_f32 v50, v50, v51
	v_cvt_pk_bf16_f32 v51, v52, v53
	s_waitcnt lgkmcnt(0)
	v_pk_add_f32 v[52:53], v[54:55], v[56:57]
	ds_bpermute_b32 v55, v97, v53
	ds_bpermute_b32 v54, v97, v52
	global_store_dwordx2 v[76:77], v[50:51], off offset:96
	v_or_b32_e32 v50, 32, v102
	v_mad_u64_u32 v[50:51], s[0:1], v50, s82, v[66:67]
	s_waitcnt lgkmcnt(0)
	v_pk_add_f32 v[52:53], v[52:53], v[54:55]
	v_add_u32_e32 v51, v100, v51
	v_pk_fma_f32 v[52:53], v[52:53], s[8:9], v[72:73] op_sel_hi:[1,0,0]
	v_lshl_add_u64 v[50:51], v[50:51], 0, v[98:99]
	v_mul_f32_e32 v54, 0x4b800000, v53
	v_cmp_gt_f32_e32 vcc, s83, v53
	v_lshl_add_u64 v[50:51], v[50:51], 0, v[68:69]
	v_readlane_b32 s84, v197, 14
	v_cndmask_b32_e32 v53, v53, v54, vcc
	v_rsq_f32_e32 v53, v53
	v_readlane_b32 s85, v197, 15
	v_readlane_b32 s78, v197, 8
	v_readlane_b32 s79, v197, 9
	v_mul_f32_e32 v54, 0x45800000, v53
	v_cndmask_b32_e32 v54, v53, v54, vcc
	v_pk_mul_f32 v[38:39], v[38:39], v[54:55] op_sel_hi:[1,0]
	v_pk_mul_f32 v[40:41], v[40:41], v[54:55] op_sel_hi:[1,0]
	v_pk_mul_f32 v[38:39], v[22:23], v[38:39]
	v_pk_mul_f32 v[40:41], v[24:25], v[40:41]
	v_cvt_pk_bf16_f32 v38, v38, v39
	v_cvt_pk_bf16_f32 v39, v40, v41
	global_store_dwordx2 v[50:51], v[38:39], off offset:64
	v_mul_f32_e32 v38, 0x4b800000, v52
	v_cmp_gt_f32_e32 vcc, s83, v52
	v_pk_mul_f32 v[30:31], v[30:31], v[54:55] op_sel_hi:[1,0]
	v_pk_mul_f32 v[32:33], v[32:33], v[54:55] op_sel_hi:[1,0]
	v_cndmask_b32_e32 v38, v52, v38, vcc
	v_rsq_f32_e32 v38, v38
	v_pk_mul_f32 v[32:33], v[20:21], v[32:33]
	v_pk_mul_f32 v[30:31], v[18:19], v[30:31]
	v_pk_mul_f32 v[46:47], v[46:47], v[54:55] op_sel_hi:[1,0]
	v_cvt_pk_bf16_f32 v30, v30, v31
	v_cvt_pk_bf16_f32 v31, v32, v33
	global_store_dwordx2 v[50:51], v[30:31], off offset:96
	v_mul_f32_e32 v30, 0x45800000, v38
	v_or_b32_e32 v31, 48, v102
	v_cndmask_b32_e32 v30, v38, v30, vcc
	v_mad_u64_u32 v[32:33], s[0:1], v31, s82, v[66:67]
	v_pk_mul_f32 v[48:49], v[48:49], v[54:55] op_sel_hi:[1,0]
	v_pk_mul_f32 v[42:43], v[42:43], v[54:55] op_sel_hi:[1,0]
	v_pk_mul_f32 v[44:45], v[44:45], v[54:55] op_sel_hi:[1,0]
	v_add_u32_e32 v33, v100, v33
	v_pk_mul_f32 v[14:15], v[14:15], v[30:31] op_sel_hi:[1,0]
	v_pk_mul_f32 v[16:17], v[16:17], v[30:31] op_sel_hi:[1,0]
	v_pk_mul_f32 v[10:11], v[10:11], v[30:31] op_sel_hi:[1,0]
	v_pk_mul_f32 v[12:13], v[12:13], v[30:31] op_sel_hi:[1,0]
	v_pk_mul_f32 v[6:7], v[6:7], v[30:31] op_sel_hi:[1,0]
	v_pk_mul_f32 v[8:9], v[8:9], v[30:31] op_sel_hi:[1,0]
	v_pk_mul_f32 v[2:3], v[2:3], v[30:31] op_sel_hi:[1,0]
	v_pk_mul_f32 v[4:5], v[4:5], v[30:31] op_sel_hi:[1,0]
	v_readlane_b32 s80, v197, 10
	v_readlane_b32 s81, v197, 11
	s_movk_i32 s84, 0xfa00
	v_pk_mul_f32 v[48:49], v[36:37], v[48:49]
	v_pk_mul_f32 v[46:47], v[34:35], v[46:47]
	v_pk_mul_f32 v[44:45], v[28:29], v[44:45]
	v_pk_mul_f32 v[42:43], v[26:27], v[42:43]
	v_lshl_add_u64 v[32:33], v[32:33], 0, v[98:99]
	v_pk_mul_f32 v[16:17], v[36:37], v[16:17]
	v_pk_mul_f32 v[14:15], v[34:35], v[14:15]
	v_pk_mul_f32 v[12:13], v[28:29], v[12:13]
	v_pk_mul_f32 v[10:11], v[26:27], v[10:11]
	v_pk_mul_f32 v[8:9], v[24:25], v[8:9]
	v_pk_mul_f32 v[6:7], v[22:23], v[6:7]
	v_pk_mul_f32 v[4:5], v[20:21], v[4:5]
	v_pk_mul_f32 v[2:3], v[18:19], v[2:3]
	s_mov_b32 s85, -1
	s_mov_b32 s79, 0x1ffffc0
	s_mov_b64 s[80:81], 0x80
	s_mov_b32 s78, 0xc0000
	v_cvt_pk_bf16_f32 v46, v46, v47
	v_cvt_pk_bf16_f32 v47, v48, v49
	v_cvt_pk_bf16_f32 v42, v42, v43
	v_cvt_pk_bf16_f32 v43, v44, v45
	v_lshl_add_u64 v[32:33], v[32:33], 0, v[68:69]
	v_cvt_pk_bf16_f32 v14, v14, v15
	v_cvt_pk_bf16_f32 v15, v16, v17
	v_cvt_pk_bf16_f32 v10, v10, v11
	v_cvt_pk_bf16_f32 v11, v12, v13
	v_cvt_pk_bf16_f32 v6, v6, v7
	v_cvt_pk_bf16_f32 v7, v8, v9
	v_cvt_pk_bf16_f32 v2, v2, v3
	v_cvt_pk_bf16_f32 v3, v4, v5
	v_readlane_b32 s73, v197, 3
	v_readlane_b32 s74, v197, 4
	v_readlane_b32 s75, v197, 5
	v_readlane_b32 s86, v197, 16
	v_readlane_b32 s87, v197, 17
	global_store_dwordx2 v[50:51], v[46:47], off
	global_store_dwordx2 v[50:51], v[42:43], off offset:32
	global_store_dwordx2 v[32:33], v[14:15], off
	global_store_dwordx2 v[32:33], v[10:11], off offset:32
	global_store_dwordx2 v[32:33], v[6:7], off offset:64
	global_store_dwordx2 v[32:33], v[2:3], off offset:96

.Ldq_skip2:
	s_mov_b64 exec, s[8:9]
	s_mov_b32 s99, 1
	ds_read_b128 v[72:75], v16
	ds_read_b128 v[76:79], v16 offset:2048
	ds_read_b128 v[106:109], v16 offset:4096
	ds_read_b128 v[112:115], v16 offset:6144
	ds_read_b128 v[116:119], v17
	ds_read_b128 v[120:123], v17 offset:2048
	ds_read_b128 v[124:127], v17 offset:4096
	ds_read_b128 v[128:131], v17 offset:6144
	s_waitcnt lgkmcnt(8)
	v_mfma_f32_16x16x32_bf16 v[84:87], v[152:155], v[102:105], v[84:87]
	v_mfma_f32_16x16x32_bf16 v[88:91], v[156:159], v[102:105], v[88:91]
	v_mfma_f32_16x16x32_bf16 v[92:95], v[160:163], v[102:105], v[92:95]
	v_mfma_f32_16x16x32_bf16 v[22:25], v[164:167], v[102:105], v[22:25]
	v_mfma_f32_16x16x32_bf16 v[38:41], v[152:155], v[132:135], v[38:41]
	v_mfma_f32_16x16x32_bf16 v[46:49], v[156:159], v[132:135], v[46:49]
	v_mfma_f32_16x16x32_bf16 v[58:61], v[160:163], v[132:135], v[58:61]
	v_mfma_f32_16x16x32_bf16 v[50:53], v[164:167], v[132:135], v[50:53]
	v_mfma_f32_16x16x32_bf16 v[42:45], v[152:155], v[138:141], v[42:45]
	v_mfma_f32_16x16x32_bf16 v[62:65], v[156:159], v[138:141], v[62:65]
	v_mfma_f32_16x16x32_bf16 v[66:69], v[160:163], v[138:141], v[66:69]
	v_mfma_f32_16x16x32_bf16 v[54:57], v[164:167], v[138:141], v[54:57]
	v_mfma_f32_16x16x32_bf16 v[34:37], v[152:155], v[142:145], v[34:37]
	v_mfma_f32_16x16x32_bf16 v[30:33], v[156:159], v[142:145], v[30:33]
	v_mfma_f32_16x16x32_bf16 v[26:29], v[160:163], v[142:145], v[26:29]
	v_mfma_f32_16x16x32_bf16 v[18:21], v[164:167], v[142:145], v[18:21]
	s_waitcnt vmcnt(6) lgkmcnt(0)
	s_barrier
	ds_read_b128 v[102:105], v8
	ds_read_b128 v[132:135], v8 offset:2048
	ds_read_b128 v[138:141], v8 offset:4096
	ds_read_b128 v[142:145], v8 offset:6144
	ds_read_b128 v[152:155], v9 offset:16384
	ds_read_b128 v[156:159], v9 offset:18432
	ds_read_b128 v[160:163], v9 offset:20480
	ds_read_b128 v[164:167], v9 offset:22528
	v_mfma_f32_16x16x32_bf16 v[84:87], v[116:119], v[72:75], v[84:87]
	v_mfma_f32_16x16x32_bf16 v[88:91], v[120:123], v[72:75], v[88:91]
	v_mfma_f32_16x16x32_bf16 v[92:95], v[124:127], v[72:75], v[92:95]
	v_mfma_f32_16x16x32_bf16 v[22:25], v[128:131], v[72:75], v[22:25]
	v_mfma_f32_16x16x32_bf16 v[38:41], v[116:119], v[76:79], v[38:41]
	v_mfma_f32_16x16x32_bf16 v[46:49], v[120:123], v[76:79], v[46:49]
	v_mfma_f32_16x16x32_bf16 v[58:61], v[124:127], v[76:79], v[58:61]
	v_mfma_f32_16x16x32_bf16 v[50:53], v[128:131], v[76:79], v[50:53]
	v_mfma_f32_16x16x32_bf16 v[42:45], v[116:119], v[106:109], v[42:45]
	v_mfma_f32_16x16x32_bf16 v[62:65], v[120:123], v[106:109], v[62:65]
	v_mfma_f32_16x16x32_bf16 v[66:69], v[124:127], v[106:109], v[66:69]
	v_mfma_f32_16x16x32_bf16 v[54:57], v[128:131], v[106:109], v[54:57]
	v_mfma_f32_16x16x32_bf16 v[34:37], v[116:119], v[112:115], v[34:37]
	v_mfma_f32_16x16x32_bf16 v[30:33], v[120:123], v[112:115], v[30:33]
	v_mfma_f32_16x16x32_bf16 v[26:29], v[124:127], v[112:115], v[26:29]
	v_mfma_f32_16x16x32_bf16 v[18:21], v[128:131], v[112:115], v[18:21]
	s_mov_b64 s[8:9], 0x700
	s_mov_b32 m0, s64
	v_lshl_add_u64 v[72:73], v[2:3], 0, s[8:9]
	global_load_lds_dwordx4 v[72:73], off
	v_lshl_add_u64 v[72:73], v[4:5], 0, s[8:9]
	s_mov_b32 m0, s71
	s_nop 0
	global_load_lds_dwordx4 v[72:73], off
	v_lshl_add_u64 v[72:73], v[6:7], 0, s[8:9]
	s_mov_b32 m0, s73
	s_mov_b64 s[8:9], 0x20700
	global_load_lds_dwordx4 v[72:73], off
	v_lshl_add_u64 v[72:73], v[6:7], 0, s[8:9]
	s_mov_b32 m0, s74
	s_mov_b64 s[8:9], 0x40700
	global_load_lds_dwordx4 v[72:73], off
	v_lshl_add_u64 v[72:73], v[6:7], 0, s[8:9]
	s_mov_b32 m0, s75
	s_mov_b64 s[8:9], 0x60700
	global_load_lds_dwordx4 v[72:73], off
	v_lshl_add_u64 v[72:73], v[6:7], 0, s[8:9]
	s_mov_b32 m0, s76
	s_nop 0
	global_load_lds_dwordx4 v[72:73], off
	ds_read_b128 v[72:75], v10
	ds_read_b128 v[76:79], v10 offset:2048
	ds_read_b128 v[106:109], v10 offset:4096
	ds_read_b128 v[112:115], v10 offset:6144
	ds_read_b128 v[116:119], v11 offset:16384
	ds_read_b128 v[120:123], v11 offset:18432
	ds_read_b128 v[124:127], v11 offset:20480
	ds_read_b128 v[128:131], v11 offset:22528
	s_waitcnt lgkmcnt(8)
	v_mfma_f32_16x16x32_bf16 v[84:87], v[152:155], v[102:105], v[84:87]
	v_mfma_f32_16x16x32_bf16 v[88:91], v[156:159], v[102:105], v[88:91]
	v_mfma_f32_16x16x32_bf16 v[92:95], v[160:163], v[102:105], v[92:95]
	v_mfma_f32_16x16x32_bf16 v[22:25], v[164:167], v[102:105], v[22:25]
	v_mfma_f32_16x16x32_bf16 v[38:41], v[152:155], v[132:135], v[38:41]
	v_mfma_f32_16x16x32_bf16 v[46:49], v[156:159], v[132:135], v[46:49]
	v_mfma_f32_16x16x32_bf16 v[58:61], v[160:163], v[132:135], v[58:61]
	v_mfma_f32_16x16x32_bf16 v[50:53], v[164:167], v[132:135], v[50:53]
	v_mfma_f32_16x16x32_bf16 v[42:45], v[152:155], v[138:141], v[42:45]
	v_mfma_f32_16x16x32_bf16 v[62:65], v[156:159], v[138:141], v[62:65]
	v_mfma_f32_16x16x32_bf16 v[66:69], v[160:163], v[138:141], v[66:69]
	v_mfma_f32_16x16x32_bf16 v[54:57], v[164:167], v[138:141], v[54:57]
	v_mfma_f32_16x16x32_bf16 v[34:37], v[152:155], v[142:145], v[34:37]
	v_mfma_f32_16x16x32_bf16 v[30:33], v[156:159], v[142:145], v[30:33]
	v_mfma_f32_16x16x32_bf16 v[26:29], v[160:163], v[142:145], v[26:29]
	v_mfma_f32_16x16x32_bf16 v[18:21], v[164:167], v[142:145], v[18:21]
	s_waitcnt vmcnt(6) lgkmcnt(0)
	s_barrier
	ds_read_b128 v[102:105], v8 offset:49152
	ds_read_b128 v[132:135], v8 offset:51200
	ds_read_b128 v[138:141], v8 offset:53248
	ds_read_b128 v[142:145], v8 offset:55296
	ds_read_b128 v[152:155], v12
	ds_read_b128 v[156:159], v12 offset:2048
	ds_read_b128 v[160:163], v12 offset:4096
	ds_read_b128 v[164:167], v12 offset:6144
	v_mfma_f32_16x16x32_bf16 v[84:87], v[116:119], v[72:75], v[84:87]
	v_mfma_f32_16x16x32_bf16 v[88:91], v[120:123], v[72:75], v[88:91]
	v_mfma_f32_16x16x32_bf16 v[92:95], v[124:127], v[72:75], v[92:95]
	v_mfma_f32_16x16x32_bf16 v[22:25], v[128:131], v[72:75], v[22:25]
	v_mfma_f32_16x16x32_bf16 v[38:41], v[116:119], v[76:79], v[38:41]
	v_mfma_f32_16x16x32_bf16 v[46:49], v[120:123], v[76:79], v[46:49]
	v_mfma_f32_16x16x32_bf16 v[58:61], v[124:127], v[76:79], v[58:61]
	v_mfma_f32_16x16x32_bf16 v[50:53], v[128:131], v[76:79], v[50:53]
	v_mfma_f32_16x16x32_bf16 v[42:45], v[116:119], v[106:109], v[42:45]
	v_mfma_f32_16x16x32_bf16 v[62:65], v[120:123], v[106:109], v[62:65]
	v_mfma_f32_16x16x32_bf16 v[66:69], v[124:127], v[106:109], v[66:69]
	v_mfma_f32_16x16x32_bf16 v[54:57], v[128:131], v[106:109], v[54:57]
	v_mfma_f32_16x16x32_bf16 v[34:37], v[116:119], v[112:115], v[34:37]
	v_mfma_f32_16x16x32_bf16 v[30:33], v[120:123], v[112:115], v[30:33]
	v_mfma_f32_16x16x32_bf16 v[26:29], v[124:127], v[112:115], v[26:29]
	v_mfma_f32_16x16x32_bf16 v[18:21], v[128:131], v[112:115], v[18:21]
	s_mov_b64 s[8:9], 0x780
	s_mov_b32 m0, s57
	v_lshl_add_u64 v[2:3], v[2:3], 0, s[8:9]
	global_load_lds_dwordx4 v[2:3], off
	v_lshl_add_u64 v[2:3], v[4:5], 0, s[8:9]
	s_mov_b32 m0, s5
	s_nop 0
	global_load_lds_dwordx4 v[2:3], off
	v_lshl_add_u64 v[2:3], v[6:7], 0, s[8:9]
	s_mov_b32 m0, s33
	s_mov_b64 s[8:9], 0x20780
	global_load_lds_dwordx4 v[2:3], off
	v_lshl_add_u64 v[2:3], v[6:7], 0, s[8:9]
	s_mov_b32 m0, s38
	s_mov_b64 s[8:9], 0x40780
	global_load_lds_dwordx4 v[2:3], off
	v_lshl_add_u64 v[2:3], v[6:7], 0, s[8:9]
	s_mov_b32 m0, s39
	s_mov_b64 s[8:9], 0x60780
	global_load_lds_dwordx4 v[2:3], off
	v_lshl_add_u64 v[2:3], v[6:7], 0, s[8:9]
	s_mov_b32 m0, s56
	s_nop 0
	global_load_lds_dwordx4 v[2:3], off
	ds_read_b128 v[2:5], v10 offset:49152
	ds_read_b128 v[72:75], v10 offset:51200
	ds_read_b128 v[76:79], v10 offset:53248
	ds_read_b128 v[106:109], v10 offset:55296
	ds_read_b128 v[112:115], v13
	ds_read_b128 v[116:119], v13 offset:2048
	ds_read_b128 v[120:123], v13 offset:4096
	ds_read_b128 v[124:127], v13 offset:6144
	s_waitcnt lgkmcnt(8)
	v_mfma_f32_16x16x32_bf16 v[84:87], v[152:155], v[102:105], v[84:87]
	v_mfma_f32_16x16x32_bf16 v[88:91], v[156:159], v[102:105], v[88:91]
	v_mfma_f32_16x16x32_bf16 v[92:95], v[160:163], v[102:105], v[92:95]
	v_mfma_f32_16x16x32_bf16 v[22:25], v[164:167], v[102:105], v[22:25]
	v_mfma_f32_16x16x32_bf16 v[38:41], v[152:155], v[132:135], v[38:41]
	v_mfma_f32_16x16x32_bf16 v[46:49], v[156:159], v[132:135], v[46:49]
	v_mfma_f32_16x16x32_bf16 v[58:61], v[160:163], v[132:135], v[58:61]
	v_mfma_f32_16x16x32_bf16 v[50:53], v[164:167], v[132:135], v[50:53]
	v_mfma_f32_16x16x32_bf16 v[42:45], v[152:155], v[138:141], v[42:45]
	v_mfma_f32_16x16x32_bf16 v[62:65], v[156:159], v[138:141], v[62:65]
	v_mfma_f32_16x16x32_bf16 v[66:69], v[160:163], v[138:141], v[66:69]
	v_mfma_f32_16x16x32_bf16 v[54:57], v[164:167], v[138:141], v[54:57]
	v_mfma_f32_16x16x32_bf16 v[34:37], v[152:155], v[142:145], v[34:37]
	v_mfma_f32_16x16x32_bf16 v[30:33], v[156:159], v[142:145], v[30:33]
	v_mfma_f32_16x16x32_bf16 v[26:29], v[160:163], v[142:145], v[26:29]
	v_mfma_f32_16x16x32_bf16 v[18:21], v[164:167], v[142:145], v[18:21]
	s_waitcnt vmcnt(6) lgkmcnt(0)
	s_barrier
	ds_read_b128 v[102:105], v14
	ds_read_b128 v[128:131], v14 offset:2048
	ds_read_b128 v[132:135], v14 offset:4096
	ds_read_b128 v[138:141], v14 offset:6144
	ds_read_b128 v[142:145], v15
	ds_read_b128 v[152:155], v15 offset:2048
	ds_read_b128 v[156:159], v15 offset:4096
	ds_read_b128 v[12:15], v15 offset:6144
	v_mfma_f32_16x16x32_bf16 v[84:87], v[112:115], v[2:5], v[84:87]
	v_mfma_f32_16x16x32_bf16 v[88:91], v[116:119], v[2:5], v[88:91]
	v_mfma_f32_16x16x32_bf16 v[92:95], v[120:123], v[2:5], v[92:95]
	v_mfma_f32_16x16x32_bf16 v[2:5], v[124:127], v[2:5], v[22:25]
	v_mfma_f32_16x16x32_bf16 v[22:25], v[112:115], v[72:75], v[38:41]
	v_mfma_f32_16x16x32_bf16 v[38:41], v[116:119], v[72:75], v[46:49]
	v_mfma_f32_16x16x32_bf16 v[46:49], v[120:123], v[72:75], v[58:61]
	v_mfma_f32_16x16x32_bf16 v[50:53], v[124:127], v[72:75], v[50:53]
	v_mfma_f32_16x16x32_bf16 v[42:45], v[112:115], v[76:79], v[42:45]
	v_mfma_f32_16x16x32_bf16 v[58:61], v[116:119], v[76:79], v[62:65]
	v_mfma_f32_16x16x32_bf16 v[62:65], v[120:123], v[76:79], v[66:69]
	v_mfma_f32_16x16x32_bf16 v[54:57], v[124:127], v[76:79], v[54:57]
	v_mfma_f32_16x16x32_bf16 v[34:37], v[112:115], v[106:109], v[34:37]
	v_mfma_f32_16x16x32_bf16 v[30:33], v[116:119], v[106:109], v[30:33]
	v_mfma_f32_16x16x32_bf16 v[26:29], v[120:123], v[106:109], v[26:29]
	v_mfma_f32_16x16x32_bf16 v[18:21], v[124:127], v[106:109], v[18:21]
	ds_read_b128 v[66:69], v16
	ds_read_b128 v[72:75], v16 offset:2048
	ds_read_b128 v[76:79], v16 offset:4096
	ds_read_b128 v[106:109], v16 offset:6144
	ds_read_b128 v[112:115], v17
	ds_read_b128 v[116:119], v17 offset:2048
	ds_read_b128 v[120:123], v17 offset:4096
	ds_read_b128 v[124:127], v17 offset:6144
	s_waitcnt lgkmcnt(8)
	v_mfma_f32_16x16x32_bf16 v[84:87], v[142:145], v[102:105], v[84:87]
	v_mfma_f32_16x16x32_bf16 v[88:91], v[152:155], v[102:105], v[88:91]
	v_mfma_f32_16x16x32_bf16 v[92:95], v[156:159], v[102:105], v[92:95]
	v_mfma_f32_16x16x32_bf16 v[2:5], v[12:15], v[102:105], v[2:5]
	v_mfma_f32_16x16x32_bf16 v[22:25], v[142:145], v[128:131], v[22:25]
	v_mfma_f32_16x16x32_bf16 v[38:41], v[152:155], v[128:131], v[38:41]
	v_mfma_f32_16x16x32_bf16 v[46:49], v[156:159], v[128:131], v[46:49]
	v_mfma_f32_16x16x32_bf16 v[50:53], v[12:15], v[128:131], v[50:53]
	v_mfma_f32_16x16x32_bf16 v[42:45], v[142:145], v[132:135], v[42:45]
	v_mfma_f32_16x16x32_bf16 v[58:61], v[152:155], v[132:135], v[58:61]
	v_mfma_f32_16x16x32_bf16 v[62:65], v[156:159], v[132:135], v[62:65]
	v_mfma_f32_16x16x32_bf16 v[54:57], v[12:15], v[132:135], v[54:57]
	v_mfma_f32_16x16x32_bf16 v[34:37], v[142:145], v[138:141], v[34:37]
	v_mfma_f32_16x16x32_bf16 v[30:33], v[152:155], v[138:141], v[30:33]
	v_mfma_f32_16x16x32_bf16 v[26:29], v[156:159], v[138:141], v[26:29]
	v_mfma_f32_16x16x32_bf16 v[12:15], v[12:15], v[138:141], v[18:21]
	s_waitcnt vmcnt(0) lgkmcnt(0)
	s_barrier
	s_mov_b64 s[8:9], exec
	v_readlane_b32 s20, v197, 0
	v_readlane_b32 s21, v197, 1
	s_and_b64 s[20:21], s[8:9], s[20:21]
	s_mov_b64 exec, s[20:21]
	s_cbranch_execz .Ldq_pskip2
	v_mov_b32_e32 v253, 0x24008
	ds_write_b32 v253, v250
.Ldq_pskip2:
	s_mov_b64 exec, s[8:9]
	s_nop 1
	ds_read_b128 v[16:19], v8
	ds_read_b128 v[102:105], v8 offset:2048
	ds_read_b128 v[128:131], v8 offset:4096
	ds_read_b128 v[132:135], v8 offset:6144
	ds_read_b128 v[138:141], v9 offset:16384
	ds_read_b128 v[142:145], v9 offset:18432
	ds_read_b128 v[152:155], v9 offset:20480
	ds_read_b128 v[6:9], v9 offset:22528
	v_mfma_f32_16x16x32_bf16 v[84:87], v[112:115], v[66:69], v[84:87]
	v_mfma_f32_16x16x32_bf16 v[88:91], v[116:119], v[66:69], v[88:91]
	v_mfma_f32_16x16x32_bf16 v[92:95], v[120:123], v[66:69], v[92:95]
	v_mfma_f32_16x16x32_bf16 v[2:5], v[124:127], v[66:69], v[2:5]
	v_mfma_f32_16x16x32_bf16 v[20:23], v[112:115], v[72:75], v[22:25]
	v_mfma_f32_16x16x32_bf16 v[38:41], v[116:119], v[72:75], v[38:41]
	v_mfma_f32_16x16x32_bf16 v[46:49], v[120:123], v[72:75], v[46:49]
	v_mfma_f32_16x16x32_bf16 v[50:53], v[124:127], v[72:75], v[50:53]
	v_mfma_f32_16x16x32_bf16 v[42:45], v[112:115], v[76:79], v[42:45]
	v_mfma_f32_16x16x32_bf16 v[58:61], v[116:119], v[76:79], v[58:61]
	v_mfma_f32_16x16x32_bf16 v[62:65], v[120:123], v[76:79], v[62:65]
	v_mfma_f32_16x16x32_bf16 v[54:57], v[124:127], v[76:79], v[54:57]
	v_mfma_f32_16x16x32_bf16 v[34:37], v[112:115], v[106:109], v[34:37]
	v_mfma_f32_16x16x32_bf16 v[30:33], v[116:119], v[106:109], v[30:33]
	v_mfma_f32_16x16x32_bf16 v[24:27], v[120:123], v[106:109], v[26:29]
	v_mfma_f32_16x16x32_bf16 v[12:15], v[124:127], v[106:109], v[12:15]
	ds_read_b128 v[66:69], v10
	ds_read_b128 v[72:75], v10 offset:2048
	ds_read_b128 v[76:79], v10 offset:4096
	ds_read_b128 v[106:109], v10 offset:6144
	ds_read_b128 v[112:115], v11 offset:16384
	ds_read_b128 v[116:119], v11 offset:18432
	ds_read_b128 v[120:123], v11 offset:20480
	ds_read_b128 v[124:127], v11 offset:22528
	s_addk_i32 s1, 0xf700
	s_waitcnt lgkmcnt(8)
	v_mfma_f32_16x16x32_bf16 v[84:87], v[138:141], v[16:19], v[84:87]
	v_mfma_f32_16x16x32_bf16 v[88:91], v[142:145], v[16:19], v[88:91]
	v_mfma_f32_16x16x32_bf16 v[92:95], v[152:155], v[16:19], v[92:95]
	v_mfma_f32_16x16x32_bf16 v[2:5], v[6:9], v[16:19], v[2:5]
	v_mfma_f32_16x16x32_bf16 v[16:19], v[138:141], v[102:105], v[20:23]
	v_mfma_f32_16x16x32_bf16 v[20:23], v[142:145], v[102:105], v[38:41]
	v_mfma_f32_16x16x32_bf16 v[38:41], v[152:155], v[102:105], v[46:49]
	v_mfma_f32_16x16x32_bf16 v[46:49], v[6:9], v[102:105], v[50:53]
	v_mfma_f32_16x16x32_bf16 v[42:45], v[138:141], v[128:131], v[42:45]
	v_mfma_f32_16x16x32_bf16 v[50:53], v[142:145], v[128:131], v[58:61]
	v_mfma_f32_16x16x32_bf16 v[58:61], v[152:155], v[128:131], v[62:65]
	v_mfma_f32_16x16x32_bf16 v[54:57], v[6:9], v[128:131], v[54:57]
	v_mfma_f32_16x16x32_bf16 v[34:37], v[138:141], v[132:135], v[34:37]
	v_mfma_f32_16x16x32_bf16 v[28:31], v[142:145], v[132:135], v[30:33]
	v_mfma_f32_16x16x32_bf16 v[24:27], v[152:155], v[132:135], v[24:27]
	v_mfma_f32_16x16x32_bf16 v[6:9], v[6:9], v[132:135], v[12:15]
	s_waitcnt vmcnt(0) lgkmcnt(0)
	s_barrier
	v_mfma_f32_16x16x32_bf16 v[10:13], v[112:115], v[66:69], v[84:87]
	v_mfma_f32_16x16x32_bf16 v[62:65], v[116:119], v[66:69], v[88:91]
	v_mfma_f32_16x16x32_bf16 v[84:87], v[120:123], v[66:69], v[92:95]
	v_mfma_f32_16x16x32_bf16 v[2:5], v[124:127], v[66:69], v[2:5]
	v_mfma_f32_16x16x32_bf16 v[14:17], v[112:115], v[72:75], v[16:19]
	v_mfma_f32_16x16x32_bf16 v[18:21], v[116:119], v[72:75], v[20:23]
	v_mfma_f32_16x16x32_bf16 v[38:41], v[120:123], v[72:75], v[38:41]
	v_mfma_f32_16x16x32_bf16 v[46:49], v[124:127], v[72:75], v[46:49]
	v_mfma_f32_16x16x32_bf16 v[42:45], v[112:115], v[76:79], v[42:45]
	v_mfma_f32_16x16x32_bf16 v[50:53], v[116:119], v[76:79], v[50:53]
	v_mfma_f32_16x16x32_bf16 v[58:61], v[120:123], v[76:79], v[58:61]
	v_mfma_f32_16x16x32_bf16 v[54:57], v[124:127], v[76:79], v[54:57]
	v_mfma_f32_16x16x32_bf16 v[32:35], v[112:115], v[106:109], v[34:37]
	v_mfma_f32_16x16x32_bf16 v[28:31], v[116:119], v[106:109], v[28:31]
	v_mfma_f32_16x16x32_bf16 v[22:25], v[120:123], v[106:109], v[24:27]
	v_mfma_f32_16x16x32_bf16 v[6:9], v[124:127], v[106:109], v[6:9]
	v_lshlrev_b32_e32 v36, 6, v83
	v_lshlrev_b32_e32 v37, 2, v110
	s_and_b32 s0, s0, 0xf00
	v_lshl_add_u32 v26, v82, 6, s1
	v_or3_b32 v66, v36, v37, s0
	s_lshl_b32 s0, s4, 4
	v_and_b32_e32 v27, 0xc0, v26
	s_and_b32 s0, s0, 0x300
	v_or3_b32 v36, s0, v27, v101
	v_lshlrev_b32_e32 v26, 4, v26
	v_and_b32_e32 v26, 0xfffff000, v26
	v_lshlrev_b32_e32 v98, 14, v36
	v_ashrrev_i32_e32 v27, 31, v26
	v_lshl_add_u64 v[36:37], s[18:19], 0, v[98:99]
	v_lshl_add_u64 v[26:27], v[26:27], 1, v[36:37]
	v_lshlrev_b32_e32 v98, 1, v66
	v_lshl_add_u64 v[26:27], v[26:27], 0, v[98:99]
	v_cvt_pk_bf16_f32 v10, v10, v11
	v_cvt_pk_bf16_f32 v11, v12, v13
	s_waitcnt lgkmcnt(0)
	s_barrier
	global_store_dwordx2 v[26:27], v[10:11], off
	v_cvt_pk_bf16_f32 v10, v62, v63
	v_cvt_pk_bf16_f32 v11, v64, v65
	global_store_dwordx2 v[26:27], v[10:11], off offset:32
	v_cvt_pk_bf16_f32 v10, v84, v85
	v_cvt_pk_bf16_f32 v11, v86, v87
	global_store_dwordx2 v[26:27], v[10:11], off offset:64
	v_add_co_u32_e32 v10, vcc, s37, v26
	v_cvt_pk_bf16_f32 v2, v2, v3
	v_cvt_pk_bf16_f32 v3, v4, v5
	v_cvt_pk_bf16_f32 v4, v14, v15
	v_cvt_pk_bf16_f32 v5, v16, v17
	v_addc_co_u32_e32 v11, vcc, 0, v27, vcc
	global_store_dwordx2 v[26:27], v[2:3], off offset:96
	v_lshl_add_u64 v[2:3], v[26:27], 0, s[68:69]
	global_store_dwordx2 v[10:11], v[4:5], off
	v_cvt_pk_bf16_f32 v4, v18, v19
	v_cvt_pk_bf16_f32 v5, v20, v21
	global_store_dwordx2 v[2:3], v[4:5], off offset:32
	v_cvt_pk_bf16_f32 v4, v38, v39
	v_cvt_pk_bf16_f32 v5, v40, v41
	global_store_dwordx2 v[2:3], v[4:5], off offset:64
	v_cvt_pk_bf16_f32 v4, v46, v47
	v_cvt_pk_bf16_f32 v5, v48, v49
	v_add_co_u32_e32 v10, vcc, s65, v26
	global_store_dwordx2 v[2:3], v[4:5], off offset:96
	v_cvt_pk_bf16_f32 v4, v42, v43
	v_cvt_pk_bf16_f32 v5, v44, v45
	v_addc_co_u32_e32 v11, vcc, 0, v27, vcc
	v_lshl_add_u64 v[2:3], v[26:27], 0, s[30:31]
	global_store_dwordx2 v[10:11], v[4:5], off
	v_cvt_pk_bf16_f32 v4, v50, v51
	v_cvt_pk_bf16_f32 v5, v52, v53
	global_store_dwordx2 v[2:3], v[4:5], off offset:32
	v_cvt_pk_bf16_f32 v4, v58, v59
	v_cvt_pk_bf16_f32 v5, v60, v61
	global_store_dwordx2 v[2:3], v[4:5], off offset:64
	v_cvt_pk_bf16_f32 v4, v54, v55
	v_cvt_pk_bf16_f32 v5, v56, v57
	v_add_co_u32_e32 v10, vcc, s78, v26
	global_store_dwordx2 v[2:3], v[4:5], off offset:96
	v_cvt_pk_bf16_f32 v4, v32, v33
	v_cvt_pk_bf16_f32 v5, v34, v35
	v_addc_co_u32_e32 v11, vcc, 0, v27, vcc
	v_lshl_add_u64 v[2:3], v[26:27], 0, s[24:25]
	global_store_dwordx2 v[10:11], v[4:5], off
	v_cvt_pk_bf16_f32 v4, v28, v29
	v_cvt_pk_bf16_f32 v5, v30, v31
	global_store_dwordx2 v[2:3], v[4:5], off offset:32
	v_cvt_pk_bf16_f32 v4, v22, v23
	v_cvt_pk_bf16_f32 v5, v24, v25
	global_store_dwordx2 v[2:3], v[4:5], off offset:64
	v_cvt_pk_bf16_f32 v4, v6, v7
	v_cvt_pk_bf16_f32 v5, v8, v9
	global_store_dwordx2 v[2:3], v[4:5], off offset:96

.Ldq_pskip3:
	s_mov_b64 exec, s[8:9]
	s_nop 1
	ds_read_b128 v[16:19], v8
	ds_read_b128 v[102:105], v8 offset:2048
	ds_read_b128 v[128:131], v8 offset:4096
	ds_read_b128 v[132:135], v8 offset:6144
	ds_read_b128 v[138:141], v9 offset:16384
	ds_read_b128 v[142:145], v9 offset:18432
	ds_read_b128 v[152:155], v9 offset:20480
	ds_read_b128 v[6:9], v9 offset:22528
	v_mfma_f32_16x16x32_bf16 v[84:87], v[112:115], v[66:69], v[84:87]
	v_mfma_f32_16x16x32_bf16 v[88:91], v[116:119], v[66:69], v[88:91]
	v_mfma_f32_16x16x32_bf16 v[92:95], v[120:123], v[66:69], v[92:95]
	v_mfma_f32_16x16x32_bf16 v[2:5], v[124:127], v[66:69], v[2:5]
	v_mfma_f32_16x16x32_bf16 v[20:23], v[112:115], v[72:75], v[22:25]
	v_mfma_f32_16x16x32_bf16 v[38:41], v[116:119], v[72:75], v[38:41]
	v_mfma_f32_16x16x32_bf16 v[46:49], v[120:123], v[72:75], v[46:49]
	v_mfma_f32_16x16x32_bf16 v[50:53], v[124:127], v[72:75], v[50:53]
	v_mfma_f32_16x16x32_bf16 v[42:45], v[112:115], v[76:79], v[42:45]
	v_mfma_f32_16x16x32_bf16 v[58:61], v[116:119], v[76:79], v[58:61]
	v_mfma_f32_16x16x32_bf16 v[62:65], v[120:123], v[76:79], v[62:65]
	v_mfma_f32_16x16x32_bf16 v[54:57], v[124:127], v[76:79], v[54:57]
	v_mfma_f32_16x16x32_bf16 v[34:37], v[112:115], v[106:109], v[34:37]
	v_mfma_f32_16x16x32_bf16 v[30:33], v[116:119], v[106:109], v[30:33]
	v_mfma_f32_16x16x32_bf16 v[24:27], v[120:123], v[106:109], v[26:29]
	v_mfma_f32_16x16x32_bf16 v[12:15], v[124:127], v[106:109], v[12:15]
	ds_read_b128 v[66:69], v10
	ds_read_b128 v[72:75], v10 offset:2048
	ds_read_b128 v[76:79], v10 offset:4096
	ds_read_b128 v[106:109], v10 offset:6144
	ds_read_b128 v[112:115], v11 offset:16384
	ds_read_b128 v[116:119], v11 offset:18432
	ds_read_b128 v[120:123], v11 offset:20480
	ds_read_b128 v[124:127], v11 offset:22528
	s_addk_i32 s1, 0xfa00
	s_waitcnt lgkmcnt(8)
	v_mfma_f32_16x16x32_bf16 v[84:87], v[138:141], v[16:19], v[84:87]
	v_mfma_f32_16x16x32_bf16 v[88:91], v[142:145], v[16:19], v[88:91]
	v_mfma_f32_16x16x32_bf16 v[92:95], v[152:155], v[16:19], v[92:95]
	v_mfma_f32_16x16x32_bf16 v[2:5], v[6:9], v[16:19], v[2:5]
	v_mfma_f32_16x16x32_bf16 v[16:19], v[138:141], v[102:105], v[20:23]
	v_mfma_f32_16x16x32_bf16 v[20:23], v[142:145], v[102:105], v[38:41]
	v_mfma_f32_16x16x32_bf16 v[38:41], v[152:155], v[102:105], v[46:49]
	v_mfma_f32_16x16x32_bf16 v[46:49], v[6:9], v[102:105], v[50:53]
	v_mfma_f32_16x16x32_bf16 v[42:45], v[138:141], v[128:131], v[42:45]
	v_mfma_f32_16x16x32_bf16 v[50:53], v[142:145], v[128:131], v[58:61]
	v_mfma_f32_16x16x32_bf16 v[58:61], v[152:155], v[128:131], v[62:65]
	v_mfma_f32_16x16x32_bf16 v[54:57], v[6:9], v[128:131], v[54:57]
	v_mfma_f32_16x16x32_bf16 v[34:37], v[138:141], v[132:135], v[34:37]
	v_mfma_f32_16x16x32_bf16 v[28:31], v[142:145], v[132:135], v[30:33]
	v_mfma_f32_16x16x32_bf16 v[24:27], v[152:155], v[132:135], v[24:27]
	v_mfma_f32_16x16x32_bf16 v[6:9], v[6:9], v[132:135], v[12:15]
	s_waitcnt vmcnt(0) lgkmcnt(0)
	s_barrier
	v_mfma_f32_16x16x32_bf16 v[10:13], v[112:115], v[66:69], v[84:87]
	v_mfma_f32_16x16x32_bf16 v[62:65], v[116:119], v[66:69], v[88:91]
	v_mfma_f32_16x16x32_bf16 v[84:87], v[120:123], v[66:69], v[92:95]
	v_mfma_f32_16x16x32_bf16 v[2:5], v[124:127], v[66:69], v[2:5]
	v_mfma_f32_16x16x32_bf16 v[14:17], v[112:115], v[72:75], v[16:19]
	v_mfma_f32_16x16x32_bf16 v[18:21], v[116:119], v[72:75], v[20:23]
	v_mfma_f32_16x16x32_bf16 v[38:41], v[120:123], v[72:75], v[38:41]
	v_mfma_f32_16x16x32_bf16 v[46:49], v[124:127], v[72:75], v[46:49]
	v_mfma_f32_16x16x32_bf16 v[42:45], v[112:115], v[76:79], v[42:45]
	v_mfma_f32_16x16x32_bf16 v[50:53], v[116:119], v[76:79], v[50:53]
	v_mfma_f32_16x16x32_bf16 v[58:61], v[120:123], v[76:79], v[58:61]
	v_mfma_f32_16x16x32_bf16 v[54:57], v[124:127], v[76:79], v[54:57]
	v_mfma_f32_16x16x32_bf16 v[32:35], v[112:115], v[106:109], v[34:37]
	v_mfma_f32_16x16x32_bf16 v[28:31], v[116:119], v[106:109], v[28:31]
	v_mfma_f32_16x16x32_bf16 v[22:25], v[120:123], v[106:109], v[24:27]
	v_mfma_f32_16x16x32_bf16 v[6:9], v[124:127], v[106:109], v[6:9]
	s_nop 1
	v_or_b32_e32 v26, s1, v101
	v_lshl_add_u32 v26, v82, 6, v26
	s_bfe_u32 s0, s0, 0x2000c
	v_mul_u32_u24_e32 v98, s0, v149
	v_ashrrev_i32_e32 v27, 31, v26
	v_lshl_add_u64 v[36:37], v[26:27], 0, v[98:99]
	v_mov_b64_e32 v[66:67], s[16:17]
	v_mad_u64_u32 v[68:69], s[0:1], v36, s70, v[66:67]
	s_lshl_b32 s0, s4, 9
	s_and_b32 s0, s0, 0x1e00
	v_mad_i32_i24 v69, v37, s70, v69
	v_lshl_or_b32 v36, v83, 7, s0
	v_mov_b32_e32 v37, v99
	v_lshl_add_u64 v[68:69], v[68:69], 0, v[36:37]
	v_lshlrev_b32_e32 v72, 4, v110
	v_mov_b32_e32 v73, v99
	v_lshl_add_u64 v[68:69], v[68:69], 0, v[72:73]
	v_cvt_pk_bf16_f32 v10, v10, v11
	v_cvt_pk_bf16_f32 v11, v12, v13
	v_cvt_pk_bf16_f32 v12, v62, v63
	v_cvt_pk_bf16_f32 v13, v64, v65
	s_waitcnt lgkmcnt(0)
	s_barrier
	global_store_dwordx4 v[68:69], v[10:13], off
	s_nop 1
	v_cvt_pk_bf16_f32 v12, v2, v3
	v_or_b32_e32 v2, 16, v26
	v_ashrrev_i32_e32 v3, 31, v2
	v_lshl_add_u64 v[2:3], v[2:3], 0, v[98:99]
	v_cvt_pk_bf16_f32 v13, v4, v5
	v_mad_u64_u32 v[4:5], s[0:1], v2, s70, v[66:67]
	v_mad_i32_i24 v5, v3, s70, v5
	v_cvt_pk_bf16_f32 v10, v84, v85
	v_cvt_pk_bf16_f32 v11, v86, v87
	v_lshl_add_u64 v[2:3], v[4:5], 0, v[36:37]
	global_store_dwordx4 v[68:69], v[10:13], off offset:64
	v_cvt_pk_bf16_f32 v4, v18, v19
	v_cvt_pk_bf16_f32 v5, v20, v21
	v_lshl_add_u64 v[10:11], v[2:3], 0, v[72:73]
	v_cvt_pk_bf16_f32 v2, v14, v15
	v_cvt_pk_bf16_f32 v3, v16, v17
	global_store_dwordx4 v[10:11], v[2:5], off
	s_nop 1
	v_cvt_pk_bf16_f32 v2, v38, v39
	v_cvt_pk_bf16_f32 v3, v40, v41
	v_cvt_pk_bf16_f32 v4, v46, v47
	v_cvt_pk_bf16_f32 v5, v48, v49
	global_store_dwordx4 v[10:11], v[2:5], off offset:64
	s_nop 1
	v_or_b32_e32 v2, 32, v26
	v_ashrrev_i32_e32 v3, 31, v2
	v_lshl_add_u64 v[2:3], v[2:3], 0, v[98:99]
	v_mad_u64_u32 v[4:5], s[0:1], v2, s70, v[66:67]
	v_mad_i32_i24 v5, v3, s70, v5
	v_lshl_add_u64 v[2:3], v[4:5], 0, v[36:37]
	v_lshl_add_u64 v[10:11], v[2:3], 0, v[72:73]
	v_cvt_pk_bf16_f32 v2, v42, v43
	v_cvt_pk_bf16_f32 v3, v44, v45
	v_cvt_pk_bf16_f32 v4, v50, v51
	v_cvt_pk_bf16_f32 v5, v52, v53
	global_store_dwordx4 v[10:11], v[2:5], off
	s_nop 1
	v_cvt_pk_bf16_f32 v2, v58, v59
	v_cvt_pk_bf16_f32 v3, v60, v61
	v_cvt_pk_bf16_f32 v4, v54, v55
	v_cvt_pk_bf16_f32 v5, v56, v57
	global_store_dwordx4 v[10:11], v[2:5], off offset:64
	s_nop 1
	v_or_b32_e32 v2, 48, v26
	v_ashrrev_i32_e32 v3, 31, v2
	v_lshl_add_u64 v[2:3], v[2:3], 0, v[98:99]
	v_mad_u64_u32 v[4:5], s[0:1], v2, s70, v[66:67]
	v_mad_i32_i24 v5, v3, s70, v5
	v_lshl_add_u64 v[2:3], v[4:5], 0, v[36:37]
	v_lshl_add_u64 v[10:11], v[2:3], 0, v[72:73]
	v_cvt_pk_bf16_f32 v2, v32, v33
	v_cvt_pk_bf16_f32 v3, v34, v35
	v_cvt_pk_bf16_f32 v4, v28, v29
	v_cvt_pk_bf16_f32 v5, v30, v31
	global_store_dwordx4 v[10:11], v[2:5], off
	s_nop 1
	v_cvt_pk_bf16_f32 v2, v22, v23
	v_cvt_pk_bf16_f32 v3, v24, v25
	v_cvt_pk_bf16_f32 v4, v6, v7
	v_cvt_pk_bf16_f32 v5, v8, v9
	global_store_dwordx4 v[10:11], v[2:5], off offset:64

.Ldq_skip4:
	s_mov_b64 exec, s[8:9]
	s_mov_b32 s99, 1
	ds_read_b128 v[92:95], v16
	ds_read_b128 v[102:105], v16 offset:2048
	ds_read_b128 v[106:109], v16 offset:4096
	ds_read_b128 v[112:115], v16 offset:6144
	ds_read_b128 v[116:119], v17
	ds_read_b128 v[120:123], v17 offset:2048
	ds_read_b128 v[124:127], v17 offset:4096
	ds_read_b128 v[160:163], v17 offset:6144
	s_waitcnt lgkmcnt(8)
	v_mfma_f32_16x16x32_bf16 v[70:73], v[138:141], v[84:87], v[70:73]
	v_mfma_f32_16x16x32_bf16 v[74:77], v[142:145], v[84:87], v[74:77]
	v_mfma_f32_16x16x32_bf16 v[78:81], v[152:155], v[84:87], v[78:81]
	v_mfma_f32_16x16x32_bf16 v[22:25], v[156:159], v[84:87], v[22:25]
	v_mfma_f32_16x16x32_bf16 v[38:41], v[138:141], v[88:91], v[38:41]
	v_mfma_f32_16x16x32_bf16 v[46:49], v[142:145], v[88:91], v[46:49]
	v_mfma_f32_16x16x32_bf16 v[58:61], v[152:155], v[88:91], v[58:61]
	v_mfma_f32_16x16x32_bf16 v[50:53], v[156:159], v[88:91], v[50:53]
	v_mfma_f32_16x16x32_bf16 v[42:45], v[138:141], v[128:131], v[42:45]
	v_mfma_f32_16x16x32_bf16 v[62:65], v[142:145], v[128:131], v[62:65]
	v_mfma_f32_16x16x32_bf16 v[66:69], v[152:155], v[128:131], v[66:69]
	v_mfma_f32_16x16x32_bf16 v[54:57], v[156:159], v[128:131], v[54:57]
	v_mfma_f32_16x16x32_bf16 v[34:37], v[138:141], v[132:135], v[34:37]
	v_mfma_f32_16x16x32_bf16 v[30:33], v[142:145], v[132:135], v[30:33]
	v_mfma_f32_16x16x32_bf16 v[26:29], v[152:155], v[132:135], v[26:29]
	v_mfma_f32_16x16x32_bf16 v[18:21], v[156:159], v[132:135], v[18:21]
	s_waitcnt vmcnt(6) lgkmcnt(0)
	s_barrier
	ds_read_b128 v[84:87], v8
	ds_read_b128 v[88:91], v8 offset:2048
	ds_read_b128 v[128:131], v8 offset:4096
	ds_read_b128 v[132:135], v8 offset:6144
	ds_read_b128 v[138:141], v9 offset:16384
	ds_read_b128 v[142:145], v9 offset:18432
	ds_read_b128 v[152:155], v9 offset:20480
	ds_read_b128 v[156:159], v9 offset:22528
	v_mfma_f32_16x16x32_bf16 v[70:73], v[116:119], v[92:95], v[70:73]
	v_mfma_f32_16x16x32_bf16 v[74:77], v[120:123], v[92:95], v[74:77]
	v_mfma_f32_16x16x32_bf16 v[78:81], v[124:127], v[92:95], v[78:81]
	v_mfma_f32_16x16x32_bf16 v[22:25], v[160:163], v[92:95], v[22:25]
	v_mfma_f32_16x16x32_bf16 v[38:41], v[116:119], v[102:105], v[38:41]
	v_mfma_f32_16x16x32_bf16 v[46:49], v[120:123], v[102:105], v[46:49]
	v_mfma_f32_16x16x32_bf16 v[58:61], v[124:127], v[102:105], v[58:61]
	v_mfma_f32_16x16x32_bf16 v[50:53], v[160:163], v[102:105], v[50:53]
	v_mfma_f32_16x16x32_bf16 v[42:45], v[116:119], v[106:109], v[42:45]
	v_mfma_f32_16x16x32_bf16 v[62:65], v[120:123], v[106:109], v[62:65]
	v_mfma_f32_16x16x32_bf16 v[66:69], v[124:127], v[106:109], v[66:69]
	v_mfma_f32_16x16x32_bf16 v[54:57], v[160:163], v[106:109], v[54:57]
	v_mfma_f32_16x16x32_bf16 v[34:37], v[116:119], v[112:115], v[34:37]
	v_mfma_f32_16x16x32_bf16 v[30:33], v[120:123], v[112:115], v[30:33]
	v_mfma_f32_16x16x32_bf16 v[26:29], v[124:127], v[112:115], v[26:29]
	v_mfma_f32_16x16x32_bf16 v[18:21], v[160:163], v[112:115], v[18:21]
	s_mov_b64 s[8:9], 0x700
	s_mov_b32 m0, s63
	v_lshl_add_u64 v[92:93], v[2:3], 0, s[8:9]
	global_load_lds_dwordx4 v[92:93], off
	v_lshl_add_u64 v[92:93], v[4:5], 0, s[8:9]
	s_mov_b32 m0, s64
	s_nop 0
	global_load_lds_dwordx4 v[92:93], off
	v_lshl_add_u64 v[92:93], v[6:7], 0, s[8:9]
	s_mov_b32 m0, s72
	s_mov_b64 s[8:9], 0x20700
	global_load_lds_dwordx4 v[92:93], off
	v_lshl_add_u64 v[92:93], v[6:7], 0, s[8:9]
	s_mov_b32 m0, s73
	s_mov_b64 s[8:9], 0x40700
	global_load_lds_dwordx4 v[92:93], off
	v_lshl_add_u64 v[92:93], v[6:7], 0, s[8:9]
	s_mov_b32 m0, s74
	s_mov_b64 s[8:9], 0x60700
	global_load_lds_dwordx4 v[92:93], off
	v_lshl_add_u64 v[92:93], v[6:7], 0, s[8:9]
	s_mov_b32 m0, s75
	s_nop 0
	global_load_lds_dwordx4 v[92:93], off
	ds_read_b128 v[92:95], v10
	ds_read_b128 v[102:105], v10 offset:2048
	ds_read_b128 v[106:109], v10 offset:4096
	ds_read_b128 v[112:115], v10 offset:6144
	ds_read_b128 v[116:119], v11 offset:16384
	ds_read_b128 v[120:123], v11 offset:18432
	ds_read_b128 v[124:127], v11 offset:20480
	ds_read_b128 v[160:163], v11 offset:22528
	s_waitcnt lgkmcnt(8)
	v_mfma_f32_16x16x32_bf16 v[70:73], v[138:141], v[84:87], v[70:73]
	v_mfma_f32_16x16x32_bf16 v[74:77], v[142:145], v[84:87], v[74:77]
	v_mfma_f32_16x16x32_bf16 v[78:81], v[152:155], v[84:87], v[78:81]
	v_mfma_f32_16x16x32_bf16 v[22:25], v[156:159], v[84:87], v[22:25]
	v_mfma_f32_16x16x32_bf16 v[38:41], v[138:141], v[88:91], v[38:41]
	v_mfma_f32_16x16x32_bf16 v[46:49], v[142:145], v[88:91], v[46:49]
	v_mfma_f32_16x16x32_bf16 v[58:61], v[152:155], v[88:91], v[58:61]
	v_mfma_f32_16x16x32_bf16 v[50:53], v[156:159], v[88:91], v[50:53]
	v_mfma_f32_16x16x32_bf16 v[42:45], v[138:141], v[128:131], v[42:45]
	v_mfma_f32_16x16x32_bf16 v[62:65], v[142:145], v[128:131], v[62:65]
	v_mfma_f32_16x16x32_bf16 v[66:69], v[152:155], v[128:131], v[66:69]
	v_mfma_f32_16x16x32_bf16 v[54:57], v[156:159], v[128:131], v[54:57]
	v_mfma_f32_16x16x32_bf16 v[34:37], v[138:141], v[132:135], v[34:37]
	v_mfma_f32_16x16x32_bf16 v[30:33], v[142:145], v[132:135], v[30:33]
	v_mfma_f32_16x16x32_bf16 v[26:29], v[152:155], v[132:135], v[26:29]
	v_mfma_f32_16x16x32_bf16 v[18:21], v[156:159], v[132:135], v[18:21]
	s_waitcnt vmcnt(6) lgkmcnt(0)
	s_barrier
	ds_read_b128 v[84:87], v8 offset:49152
	ds_read_b128 v[88:91], v8 offset:51200
	ds_read_b128 v[128:131], v8 offset:53248
	ds_read_b128 v[132:135], v8 offset:55296
	ds_read_b128 v[138:141], v12
	ds_read_b128 v[142:145], v12 offset:2048
	ds_read_b128 v[152:155], v12 offset:4096
	ds_read_b128 v[156:159], v12 offset:6144
	v_mfma_f32_16x16x32_bf16 v[70:73], v[116:119], v[92:95], v[70:73]
	v_mfma_f32_16x16x32_bf16 v[74:77], v[120:123], v[92:95], v[74:77]
	v_mfma_f32_16x16x32_bf16 v[78:81], v[124:127], v[92:95], v[78:81]
	v_mfma_f32_16x16x32_bf16 v[22:25], v[160:163], v[92:95], v[22:25]
	v_mfma_f32_16x16x32_bf16 v[38:41], v[116:119], v[102:105], v[38:41]
	v_mfma_f32_16x16x32_bf16 v[46:49], v[120:123], v[102:105], v[46:49]
	v_mfma_f32_16x16x32_bf16 v[58:61], v[124:127], v[102:105], v[58:61]
	v_mfma_f32_16x16x32_bf16 v[50:53], v[160:163], v[102:105], v[50:53]
	v_mfma_f32_16x16x32_bf16 v[42:45], v[116:119], v[106:109], v[42:45]
	v_mfma_f32_16x16x32_bf16 v[62:65], v[120:123], v[106:109], v[62:65]
	v_mfma_f32_16x16x32_bf16 v[66:69], v[124:127], v[106:109], v[66:69]
	v_mfma_f32_16x16x32_bf16 v[54:57], v[160:163], v[106:109], v[54:57]
	v_mfma_f32_16x16x32_bf16 v[34:37], v[116:119], v[112:115], v[34:37]
	v_mfma_f32_16x16x32_bf16 v[30:33], v[120:123], v[112:115], v[30:33]
	v_mfma_f32_16x16x32_bf16 v[26:29], v[124:127], v[112:115], v[26:29]
	v_mfma_f32_16x16x32_bf16 v[18:21], v[160:163], v[112:115], v[18:21]
	s_mov_b64 s[8:9], 0x780
	s_mov_b32 m0, s56
	v_lshl_add_u64 v[2:3], v[2:3], 0, s[8:9]
	global_load_lds_dwordx4 v[2:3], off
	v_lshl_add_u64 v[2:3], v[4:5], 0, s[8:9]
	s_mov_b32 m0, s4
	s_nop 0
	global_load_lds_dwordx4 v[2:3], off
	v_lshl_add_u64 v[2:3], v[6:7], 0, s[8:9]
	s_mov_b32 m0, s5
	s_mov_b64 s[4:5], 0x20780
	global_load_lds_dwordx4 v[2:3], off
	v_lshl_add_u64 v[2:3], v[6:7], 0, s[4:5]
	s_mov_b32 m0, s33
	s_mov_b64 s[4:5], 0x40780
	global_load_lds_dwordx4 v[2:3], off
	v_lshl_add_u64 v[2:3], v[6:7], 0, s[4:5]
	s_mov_b32 m0, s38
	s_mov_b64 s[4:5], 0x60780
	global_load_lds_dwordx4 v[2:3], off
	v_lshl_add_u64 v[2:3], v[6:7], 0, s[4:5]
	s_mov_b32 m0, s39
	s_nop 0
	global_load_lds_dwordx4 v[2:3], off
	ds_read_b128 v[2:5], v10 offset:49152
	ds_read_b128 v[92:95], v10 offset:51200
	ds_read_b128 v[102:105], v10 offset:53248
	ds_read_b128 v[106:109], v10 offset:55296
	ds_read_b128 v[112:115], v13
	ds_read_b128 v[116:119], v13 offset:2048
	ds_read_b128 v[120:123], v13 offset:4096
	ds_read_b128 v[124:127], v13 offset:6144
	s_waitcnt lgkmcnt(8)
	v_mfma_f32_16x16x32_bf16 v[70:73], v[138:141], v[84:87], v[70:73]
	v_mfma_f32_16x16x32_bf16 v[74:77], v[142:145], v[84:87], v[74:77]
	v_mfma_f32_16x16x32_bf16 v[78:81], v[152:155], v[84:87], v[78:81]
	v_mfma_f32_16x16x32_bf16 v[22:25], v[156:159], v[84:87], v[22:25]
	v_mfma_f32_16x16x32_bf16 v[38:41], v[138:141], v[88:91], v[38:41]
	v_mfma_f32_16x16x32_bf16 v[46:49], v[142:145], v[88:91], v[46:49]
	v_mfma_f32_16x16x32_bf16 v[58:61], v[152:155], v[88:91], v[58:61]
	v_mfma_f32_16x16x32_bf16 v[50:53], v[156:159], v[88:91], v[50:53]
	v_mfma_f32_16x16x32_bf16 v[42:45], v[138:141], v[128:131], v[42:45]
	v_mfma_f32_16x16x32_bf16 v[62:65], v[142:145], v[128:131], v[62:65]
	v_mfma_f32_16x16x32_bf16 v[66:69], v[152:155], v[128:131], v[66:69]
	v_mfma_f32_16x16x32_bf16 v[54:57], v[156:159], v[128:131], v[54:57]
	v_mfma_f32_16x16x32_bf16 v[34:37], v[138:141], v[132:135], v[34:37]
	v_mfma_f32_16x16x32_bf16 v[30:33], v[142:145], v[132:135], v[30:33]
	v_mfma_f32_16x16x32_bf16 v[26:29], v[152:155], v[132:135], v[26:29]
	v_mfma_f32_16x16x32_bf16 v[18:21], v[156:159], v[132:135], v[18:21]
	s_waitcnt vmcnt(6) lgkmcnt(0)
	s_barrier
	ds_read_b128 v[84:87], v14
	ds_read_b128 v[88:91], v14 offset:2048
	ds_read_b128 v[128:131], v14 offset:4096
	ds_read_b128 v[132:135], v14 offset:6144
	ds_read_b128 v[138:141], v15
	ds_read_b128 v[142:145], v15 offset:2048
	ds_read_b128 v[152:155], v15 offset:4096
	ds_read_b128 v[12:15], v15 offset:6144
	v_mfma_f32_16x16x32_bf16 v[70:73], v[112:115], v[2:5], v[70:73]
	v_mfma_f32_16x16x32_bf16 v[74:77], v[116:119], v[2:5], v[74:77]
	v_mfma_f32_16x16x32_bf16 v[78:81], v[120:123], v[2:5], v[78:81]
	v_mfma_f32_16x16x32_bf16 v[2:5], v[124:127], v[2:5], v[22:25]
	v_mfma_f32_16x16x32_bf16 v[22:25], v[112:115], v[92:95], v[38:41]
	v_mfma_f32_16x16x32_bf16 v[38:41], v[116:119], v[92:95], v[46:49]
	v_mfma_f32_16x16x32_bf16 v[46:49], v[120:123], v[92:95], v[58:61]
	v_mfma_f32_16x16x32_bf16 v[50:53], v[124:127], v[92:95], v[50:53]
	v_mfma_f32_16x16x32_bf16 v[42:45], v[112:115], v[102:105], v[42:45]
	v_mfma_f32_16x16x32_bf16 v[58:61], v[116:119], v[102:105], v[62:65]
	v_mfma_f32_16x16x32_bf16 v[62:65], v[120:123], v[102:105], v[66:69]
	v_mfma_f32_16x16x32_bf16 v[54:57], v[124:127], v[102:105], v[54:57]
	v_mfma_f32_16x16x32_bf16 v[34:37], v[112:115], v[106:109], v[34:37]
	v_mfma_f32_16x16x32_bf16 v[30:33], v[116:119], v[106:109], v[30:33]
	v_mfma_f32_16x16x32_bf16 v[26:29], v[120:123], v[106:109], v[26:29]
	v_mfma_f32_16x16x32_bf16 v[18:21], v[124:127], v[106:109], v[18:21]
	ds_read_b128 v[66:69], v16
	ds_read_b128 v[92:95], v16 offset:2048
	ds_read_b128 v[102:105], v16 offset:4096
	ds_read_b128 v[106:109], v16 offset:6144
	ds_read_b128 v[112:115], v17
	ds_read_b128 v[116:119], v17 offset:2048
	ds_read_b128 v[120:123], v17 offset:4096
	ds_read_b128 v[124:127], v17 offset:6144
	s_waitcnt lgkmcnt(8)
	v_mfma_f32_16x16x32_bf16 v[70:73], v[138:141], v[84:87], v[70:73]
	v_mfma_f32_16x16x32_bf16 v[74:77], v[142:145], v[84:87], v[74:77]
	v_mfma_f32_16x16x32_bf16 v[78:81], v[152:155], v[84:87], v[78:81]
	v_mfma_f32_16x16x32_bf16 v[2:5], v[12:15], v[84:87], v[2:5]
	v_mfma_f32_16x16x32_bf16 v[22:25], v[138:141], v[88:91], v[22:25]
	v_mfma_f32_16x16x32_bf16 v[38:41], v[142:145], v[88:91], v[38:41]
	v_mfma_f32_16x16x32_bf16 v[46:49], v[152:155], v[88:91], v[46:49]
	v_mfma_f32_16x16x32_bf16 v[50:53], v[12:15], v[88:91], v[50:53]
	v_mfma_f32_16x16x32_bf16 v[42:45], v[138:141], v[128:131], v[42:45]
	v_mfma_f32_16x16x32_bf16 v[58:61], v[142:145], v[128:131], v[58:61]
	v_mfma_f32_16x16x32_bf16 v[62:65], v[152:155], v[128:131], v[62:65]
	v_mfma_f32_16x16x32_bf16 v[54:57], v[12:15], v[128:131], v[54:57]
	v_mfma_f32_16x16x32_bf16 v[34:37], v[138:141], v[132:135], v[34:37]
	v_mfma_f32_16x16x32_bf16 v[30:33], v[142:145], v[132:135], v[30:33]
	v_mfma_f32_16x16x32_bf16 v[26:29], v[152:155], v[132:135], v[26:29]
	v_mfma_f32_16x16x32_bf16 v[12:15], v[12:15], v[132:135], v[18:21]
	s_waitcnt vmcnt(0) lgkmcnt(0)
	s_barrier
	s_mov_b64 s[4:5], exec
	v_readlane_b32 s8, v197, 0
	v_readlane_b32 s9, v197, 1
	s_and_b64 s[8:9], s[4:5], s[8:9]
	s_mov_b64 exec, s[8:9]
	s_cbranch_execz .Ldq_pskip4
	v_mov_b32_e32 v253, 0x24008
	ds_write_b32 v253, v250
.Ldq_pskip4:
	s_mov_b64 exec, s[4:5]
	s_nop 1
	ds_read_b128 v[16:19], v8
	ds_read_b128 v[84:87], v8 offset:2048
	ds_read_b128 v[88:91], v8 offset:4096
	ds_read_b128 v[128:131], v8 offset:6144
	ds_read_b128 v[132:135], v9 offset:16384
	ds_read_b128 v[138:141], v9 offset:18432
	ds_read_b128 v[142:145], v9 offset:20480
	ds_read_b128 v[6:9], v9 offset:22528
	v_mfma_f32_16x16x32_bf16 v[70:73], v[112:115], v[66:69], v[70:73]
	v_mfma_f32_16x16x32_bf16 v[74:77], v[116:119], v[66:69], v[74:77]
	v_mfma_f32_16x16x32_bf16 v[78:81], v[120:123], v[66:69], v[78:81]
	v_mfma_f32_16x16x32_bf16 v[2:5], v[124:127], v[66:69], v[2:5]
	v_mfma_f32_16x16x32_bf16 v[20:23], v[112:115], v[92:95], v[22:25]
	v_mfma_f32_16x16x32_bf16 v[38:41], v[116:119], v[92:95], v[38:41]
	v_mfma_f32_16x16x32_bf16 v[46:49], v[120:123], v[92:95], v[46:49]
	v_mfma_f32_16x16x32_bf16 v[50:53], v[124:127], v[92:95], v[50:53]
	v_mfma_f32_16x16x32_bf16 v[42:45], v[112:115], v[102:105], v[42:45]
	v_mfma_f32_16x16x32_bf16 v[58:61], v[116:119], v[102:105], v[58:61]
	v_mfma_f32_16x16x32_bf16 v[62:65], v[120:123], v[102:105], v[62:65]
	v_mfma_f32_16x16x32_bf16 v[54:57], v[124:127], v[102:105], v[54:57]
	v_mfma_f32_16x16x32_bf16 v[34:37], v[112:115], v[106:109], v[34:37]
	v_mfma_f32_16x16x32_bf16 v[30:33], v[116:119], v[106:109], v[30:33]
	v_mfma_f32_16x16x32_bf16 v[24:27], v[120:123], v[106:109], v[26:29]
	v_mfma_f32_16x16x32_bf16 v[12:15], v[124:127], v[106:109], v[12:15]
	ds_read_b128 v[66:69], v10
	ds_read_b128 v[92:95], v10 offset:2048
	ds_read_b128 v[102:105], v10 offset:4096
	ds_read_b128 v[106:109], v10 offset:6144
	ds_read_b128 v[112:115], v11 offset:16384
	ds_read_b128 v[116:119], v11 offset:18432
	ds_read_b128 v[120:123], v11 offset:20480
	ds_read_b128 v[124:127], v11 offset:22528
	s_waitcnt lgkmcnt(8)
	v_mfma_f32_16x16x32_bf16 v[70:73], v[132:135], v[16:19], v[70:73]
	v_mfma_f32_16x16x32_bf16 v[74:77], v[138:141], v[16:19], v[74:77]
	v_mfma_f32_16x16x32_bf16 v[152:155], v[142:145], v[16:19], v[78:81]
	v_mfma_f32_16x16x32_bf16 v[2:5], v[6:9], v[16:19], v[2:5]
	v_mfma_f32_16x16x32_bf16 v[16:19], v[132:135], v[84:87], v[20:23]
	v_mfma_f32_16x16x32_bf16 v[20:23], v[138:141], v[84:87], v[38:41]
	v_mfma_f32_16x16x32_bf16 v[38:41], v[142:145], v[84:87], v[46:49]
	v_mfma_f32_16x16x32_bf16 v[46:49], v[6:9], v[84:87], v[50:53]
	v_mfma_f32_16x16x32_bf16 v[42:45], v[132:135], v[88:91], v[42:45]
	v_mfma_f32_16x16x32_bf16 v[84:87], v[138:141], v[88:91], v[58:61]
	v_mfma_f32_16x16x32_bf16 v[156:159], v[142:145], v[88:91], v[62:65]
	v_mfma_f32_16x16x32_bf16 v[88:91], v[6:9], v[88:91], v[54:57]
	v_mfma_f32_16x16x32_bf16 v[28:31], v[138:141], v[128:131], v[30:33]
	v_mfma_f32_16x16x32_bf16 v[24:27], v[142:145], v[128:131], v[24:27]
	v_mfma_f32_16x16x32_bf16 v[132:135], v[132:135], v[128:131], v[34:37]
	v_mfma_f32_16x16x32_bf16 v[128:131], v[6:9], v[128:131], v[12:15]
	s_waitcnt vmcnt(0) lgkmcnt(0)
	s_barrier
	v_mfma_f32_16x16x32_bf16 v[78:81], v[112:115], v[66:69], v[70:73]
	v_mfma_f32_16x16x32_bf16 v[74:77], v[116:119], v[66:69], v[74:77]
	v_mfma_f32_16x16x32_bf16 v[70:73], v[120:123], v[66:69], v[152:155]
	v_mfma_f32_16x16x32_bf16 v[66:69], v[124:127], v[66:69], v[2:5]
	v_mfma_f32_16x16x32_bf16 v[62:65], v[112:115], v[92:95], v[16:19]
	v_mfma_f32_16x16x32_bf16 v[58:61], v[116:119], v[92:95], v[20:23]
	v_mfma_f32_16x16x32_bf16 v[54:57], v[120:123], v[92:95], v[38:41]
	v_mfma_f32_16x16x32_bf16 v[50:53], v[124:127], v[92:95], v[46:49]
	v_mfma_f32_16x16x32_bf16 v[46:49], v[112:115], v[102:105], v[42:45]
	v_mfma_f32_16x16x32_bf16 v[42:45], v[116:119], v[102:105], v[84:87]
	v_mfma_f32_16x16x32_bf16 v[38:41], v[120:123], v[102:105], v[156:159]
	v_mfma_f32_16x16x32_bf16 v[34:37], v[124:127], v[102:105], v[88:91]
	v_mfma_f32_16x16x32_bf16 v[14:17], v[112:115], v[106:109], v[132:135]
	v_mfma_f32_16x16x32_bf16 v[10:13], v[116:119], v[106:109], v[28:31]
	v_mfma_f32_16x16x32_bf16 v[6:9], v[120:123], v[106:109], v[24:27]
	v_mfma_f32_16x16x32_bf16 v[2:5], v[124:127], v[106:109], v[128:131]
	v_readlane_b32 s8, v197, 2
	v_lshl_or_b32 v100, v83, 6, s1
	v_readlane_b32 s11, v197, 5
	v_readlane_b32 s13, v197, 7
	s_movk_i32 s1, 0x300
	v_readlane_b32 s10, v197, 4
	v_readlane_b32 s12, v197, 6
	v_mov_b32_e32 v18, s13
	v_mov_b32_e32 v19, s11
	v_cmp_gt_i32_e32 vcc, s1, v100
	v_lshl_add_u32 v98, v82, 6, s0
	v_mov_b32_e32 v20, s10
	v_cndmask_b32_e32 v19, v18, v19, vcc
	v_mov_b32_e32 v18, s12
	v_and_b32_e32 v82, 0xfc0, v98
	v_mov_b32_e32 v83, v99
	v_cndmask_b32_e32 v18, v18, v20, vcc
	v_lshlrev_b32_e32 v84, 4, v110
	v_mov_b32_e32 v85, v99
	v_lshl_add_u64 v[86:87], s[46:47], 0, v[82:83]
	v_lshl_add_u64 v[82:83], s[34:35], 0, v[82:83]
	s_waitcnt lgkmcnt(0)
	s_barrier
	v_lshl_add_u64 v[18:19], v[18:19], 0, v[84:85]
	v_lshl_add_u64 v[106:107], v[82:83], 0, v[84:85]
	v_lshlrev_b32_e32 v82, 6, v101
	v_mov_b32_e32 v83, v99
	global_load_dwordx4 v[30:33], v[18:19], off
	global_load_dwordx4 v[26:29], v[18:19], off offset:64
	global_load_dwordx4 v[22:25], v[18:19], off offset:128
	s_nop 0
	global_load_dwordx4 v[18:21], v[18:19], off offset:192
	v_lshl_add_u64 v[104:105], v[86:87], 0, v[84:85]
	v_lshl_add_u64 v[86:87], s[46:47], 0, v[82:83]
	v_lshl_add_u64 v[82:83], s[34:35], 0, v[82:83]
	v_lshl_add_u64 v[86:87], v[86:87], 0, v[84:85]
	v_lshl_add_u64 v[82:83], v[82:83], 0, v[84:85]
	global_load_dwordx4 v[90:93], v[104:105], off
	global_load_dwordx4 v[94:97], v[106:107], off
	s_nop 0
	global_load_dwordx4 v[86:89], v[86:87], off
	s_nop 0
	global_load_dwordx4 v[82:85], v[82:83], off
	v_and_b32_e32 v102, 64, v150
	v_mov_b32_e32 v108, v79
	v_mov_b32_e32 v109, v75
	v_add_u32_e32 v112, 64, v102
	v_mov_b32_e32 v102, v78
	v_mov_b32_e32 v103, v74
	v_pk_mul_f32 v[108:109], v[108:109], v[108:109]
	v_mov_b32_e32 v114, v71
	v_pk_fma_f32 v[102:103], v[102:103], v[102:103], v[108:109]
	v_mov_b32_e32 v108, v80
	v_mov_b32_e32 v109, v76
	v_pk_fma_f32 v[102:103], v[108:109], v[108:109], v[102:103]
	v_mov_b32_e32 v108, v81
	v_mov_b32_e32 v109, v77
	v_mov_b32_e32 v115, v67
	s_movk_i32 s0, 0x2ff
	v_or_b32_e32 v113, v98, v101
	v_xor_b32_e32 v101, 16, v150
	v_pk_fma_f32 v[102:103], v[108:109], v[108:109], v[102:103]
	v_mov_b32_e32 v108, v70
	v_mov_b32_e32 v109, v66
	v_pk_mul_f32 v[114:115], v[114:115], v[114:115]
	v_cmp_lt_i32_e32 vcc, s0, v100
	v_cmp_lt_i32_e64 s[0:1], v101, v112
	v_pk_fma_f32 v[108:109], v[108:109], v[108:109], v[114:115]
	v_mov_b32_e32 v114, v72
	v_mov_b32_e32 v115, v68
	v_cndmask_b32_e64 v101, v150, v101, s[0:1]
	v_pk_fma_f32 v[108:109], v[114:115], v[114:115], v[108:109]
	v_mov_b32_e32 v114, v73
	v_mov_b32_e32 v115, v69
	v_lshlrev_b32_e32 v111, 2, v101
	v_pk_fma_f32 v[108:109], v[114:115], v[114:115], v[108:109]
	v_add_f32_e32 v101, v102, v103
	v_add_f32_e32 v101, v101, v108
	v_add_f32_e32 v101, v101, v109
	ds_bpermute_b32 v102, v111, v101
	v_xor_b32_e32 v103, 32, v150
	v_cmp_lt_i32_e64 s[0:1], v103, v112
	v_ashrrev_i32_e32 v98, 12, v98
	v_readlane_b32 s9, v197, 3
	v_cndmask_b32_e64 v103, v150, v103, s[0:1]
	v_lshlrev_b32_e32 v112, 2, v103
	s_waitcnt lgkmcnt(0)
	v_add_f32_e32 v101, v101, v102
	ds_bpermute_b32 v108, v112, v101
	v_mul_hi_i32_i24_e32 v103, 0x1100, v98
	v_mul_i32_i24_e32 v102, 0x1100, v98
	v_mov_b32_e32 v98, v100
	v_readlane_b32 s14, v197, 8
	s_waitcnt lgkmcnt(0)
	v_add_f32_e32 v101, v101, v108
	v_fmamk_f32 v101, v101, 0x3c800000, v137
	v_cmp_gt_f32_e64 s[0:1], s83, v101
	v_readlane_b32 s15, v197, 9
	v_readlane_b32 s16, v197, 10
	v_readlane_b32 s17, v197, 11
	v_readlane_b32 s18, v197, 12
	v_readlane_b32 s19, v197, 13
	v_readlane_b32 s20, v197, 14
	v_readlane_b32 s21, v197, 15
	v_readlane_b32 s22, v197, 16
	v_readlane_b32 s23, v197, 17
	s_and_saveexec_b64 s[4:5], vcc
	s_xor_b64 s[4:5], exec, s[4:5]
	s_cbranch_execz .LBB0_318
	v_readlane_b32 s8, v196, 6
	v_and_b32_e32 v108, 0xfcf, v113
	v_mov_b32_e32 v109, v99
	v_readlane_b32 s14, v196, 12
	v_readlane_b32 s15, v196, 13
	v_lshl_add_u64 v[108:109], v[102:103], 0, v[108:109]
	v_readlane_b32 s9, v196, 7
	v_mov_b64_e32 v[114:115], s[14:15]
	v_mad_u64_u32 v[114:115], s[38:39], v108, s82, v[114:115]
	v_mov_b32_e32 v108, v115
	v_mad_u64_u32 v[108:109], s[38:39], v109, s82, v[108:109]
	v_mov_b32_e32 v115, v108
	v_lshl_add_u64 v[108:109], v[98:99], 1, v[114:115]
	v_readlane_b32 s10, v196, 8
	v_readlane_b32 s11, v196, 9
	v_readlane_b32 s12, v196, 10
	v_readlane_b32 s13, v196, 11
	v_readlane_b32 s16, v196, 14
	v_readlane_b32 s17, v196, 15
	v_readlane_b32 s18, v196, 16
	v_readlane_b32 s19, v196, 17
	v_readlane_b32 s20, v196, 18
	v_readlane_b32 s21, v196, 19
	v_readlane_b32 s22, v196, 20
	v_readlane_b32 s23, v196, 21
	v_lshl_add_u64 v[108:109], v[108:109], 0, s[84:85]
